# attention: staging loads at QK^T slots 0/8/16/24
# speedup vs baseline: 1.0009x; 1.0009x over previous
; __device__ __forceinline__ void partialSM(f32x16& p0, f32x16& p1, float mC) {
;   (void)mC; (void)p1;
;   for (int r = 0; r < 16; ++r) p0[r] = __builtin_amdgcn_exp2f(p0[r]);
; }
; __device__ __forceinline__ void finishSM(f32x16& p0, f32x16& p1, float& l_reg, bf16x8& pa0, bf16x8& pa1, bf16x8& pa2, bf16x8& pa3) {
;   for (int r = 0; r < 16; ++r) p1[r] = __builtin_amdgcn_exp2f(p1[r]);
;   float ps = 0; for (int r = 0; r < 16; ++r) ps += p0[r]; for (int r = 0; r < 16; ++r) ps += p1[r];
;   { auto rr = __builtin_amdgcn_permlane32_swap(__float_as_uint(ps), __float_as_uint(ps), false, false);
;     ps = __uint_as_float(rr[0]) + __uint_as_float(rr[1]); }
;   l_reg += ps;
;     ...
;   PK4(p0, 0, pa0); PK4(p0, 8, pa1); PK4(p1, 0, pa2); PK4(p1, 8, pa3);
;     ...
; }
; __device__ __forceinline__ void qkt(f32x16& p0, f32x16& p1, const bf16* Ks, const bf16x8* qr, int r32, int hi, const f32x16& negm) {
; #pragma unroll
;   for (int d0 = 0; d0 < 8; ++d0) { int cb = (d0 * 16 + hi * 8) * 2;
;     bf16x8 b0 = *reinterpret_cast<const bf16x8*>((const char*)Ks + KSWZ(r32, cb));
;     bf16x8 b1 = *reinterpret_cast<const bf16x8*>((const char*)Ks + KSWZ(32 + r32, cb));
;     if (d0 == 0) { p0 = __builtin_amdgcn_mfma_f32_32x32x16_bf16(b0, qr[0], negm, 0, 0, 0); p1 = __builtin_amdgcn_mfma_f32_32x32x16_bf16(b1, qr[0], negm, 0, 0, 0); }
;     else { p0 = __builtin_amdgcn_mfma_f32_32x32x16_bf16(b0, qr[d0], p0, 0, 0, 0); p1 = __builtin_amdgcn_mfma_f32_32x32x16_bf16(b1, qr[d0], p1, 0, 0, 0); } }
; }
; __device__ __forceinline__ int v_st(int k, int c) { const int kk = (k & ~0xC) | ((k & 4) << 1) | ((k & 8) >> 1); return ((kk >> 3) * 4 + (c >> 5)) * 512 + ((kk & 7) * 32 + (c & 31)) * 2; }
; __device__ __forceinline__ int v_rd_base(int lane) { return ((lane & 3) << 3) | (((lane >> 2) & 3) << 6) | (((lane >> 4) & 1) << 5) | (((lane >> 5) & 1) << 8); }
; template <int OFF> __device__ __forceinline__ s16x4 tr_read(int vb) {
;   s16x4 r; asm volatile("ds_read_b64_tr_b16 %0, %1 offset:%2" : "=&v"(r) : "v"(vb), "i"(OFF) : "memory"); return r;
; }
; template <int D0> __device__ __forceinline__ void pv_one(f32x16& od, int vb, bf16x8 pa0, bf16x8 pa1, bf16x8 pa2, bf16x8 pa3) {
;   const s16x4 l0 = tr_read<v_rd_off(D0, 0, 0)>(vb), h0 = tr_read<v_rd_off(D0, 0, 1)>(vb), l1 = tr_read<v_rd_off(D0, 1, 0)>(vb), h1 = tr_read<v_rd_off(D0, 1, 1)>(vb);
.Lattn_loop:
	s_barrier
	s_waitcnt lgkmcnt(3)
	v_mfma_f32_16x16x32_bf16 v[114:117], v[178:181], v[146:149], v[2:5]
	v_add_f32_e32 v250, v82, v250
	s_add_u32 s98, s98, 0x8000
	s_addc_u32 s99, s99, 0
	s_add_u32 s100, s100, 0x8000
	s_addc_u32 s101, s101, 0
	s_add_u32 m0, s79, 0
	s_nop 0
	global_load_lds_dwordx4 v246, s[98:99]
	v_mfma_f32_16x16x32_bf16 v[118:121], v[178:181], v[162:165], v[2:5]
	ds_read_b128 v[178:181], v235 offset:16384
	v_add_f32_e32 v250, v83, v250
	v_add_f32_e32 v250, v84, v250
	s_waitcnt lgkmcnt(3)
	v_mfma_f32_16x16x32_bf16 v[122:125], v[182:185], v[146:149], v[2:5]
	v_add_f32_e32 v250, v85, v250
	v_mfma_f32_16x16x32_bf16 v[126:129], v[182:185], v[162:165], v[2:5]
	ds_read_b128 v[182:185], v235 offset:20480
	v_add_f32_e32 v250, v90, v250
	v_add_f32_e32 v250, v91, v250
	s_waitcnt lgkmcnt(3)
	v_mfma_f32_16x16x32_bf16 v[130:133], v[186:189], v[146:149], v[2:5]
	v_add_f32_e32 v250, v92, v250
	v_mfma_f32_16x16x32_bf16 v[134:137], v[186:189], v[162:165], v[2:5]
	ds_read_b128 v[186:189], v235 offset:24576
	v_add_f32_e32 v250, v93, v250
	v_cvt_pk_bf16_f32 v82, v82, v83
	s_waitcnt lgkmcnt(3)
	v_mfma_f32_16x16x32_bf16 v[138:141], v[190:193], v[146:149], v[2:5]
	v_cvt_pk_bf16_f32 v83, v84, v85
	v_mfma_f32_16x16x32_bf16 v[142:145], v[190:193], v[162:165], v[2:5]
	ds_read_b128 v[190:193], v235 offset:28672
	v_cvt_pk_bf16_f32 v84, v90, v91
	v_cvt_pk_bf16_f32 v85, v92, v93
	s_waitcnt lgkmcnt(3)
	v_mfma_f32_16x16x32_bf16 v[114:117], v[178:181], v[150:153], v[114:117]
	v_add_f32_e32 v251, v86, v251
	s_add_u32 m0, s79, 1024
	s_nop 0
	global_load_lds_dwordx4 v247, s[98:99]
	v_mfma_f32_16x16x32_bf16 v[118:121], v[178:181], v[166:169], v[118:121]
	ds_read_b128 v[178:181], v236 offset:16384
	v_add_f32_e32 v251, v87, v251
	v_add_f32_e32 v251, v88, v251
	s_waitcnt lgkmcnt(3)
	v_mfma_f32_16x16x32_bf16 v[122:125], v[182:185], v[150:153], v[122:125]
	v_add_f32_e32 v251, v89, v251
	v_mfma_f32_16x16x32_bf16 v[126:129], v[182:185], v[166:169], v[126:129]
	ds_read_b128 v[182:185], v236 offset:20480
	v_add_f32_e32 v251, v94, v251
	v_add_f32_e32 v251, v95, v251
	s_waitcnt lgkmcnt(3)
	v_mfma_f32_16x16x32_bf16 v[130:133], v[186:189], v[150:153], v[130:133]
	v_add_f32_e32 v251, v96, v251
	v_mfma_f32_16x16x32_bf16 v[134:137], v[186:189], v[166:169], v[134:137]
	ds_read_b128 v[186:189], v236 offset:24576
	v_add_f32_e32 v251, v97, v251
	v_cvt_pk_bf16_f32 v86, v86, v87
	s_waitcnt lgkmcnt(3)
	v_mfma_f32_16x16x32_bf16 v[138:141], v[190:193], v[150:153], v[138:141]
	v_cvt_pk_bf16_f32 v87, v88, v89
	v_mfma_f32_16x16x32_bf16 v[142:145], v[190:193], v[166:169], v[142:145]
	ds_read_b128 v[190:193], v236 offset:28672
	v_cvt_pk_bf16_f32 v88, v94, v95
	v_cvt_pk_bf16_f32 v89, v96, v97
	s_waitcnt lgkmcnt(3)
	v_mfma_f32_16x16x32_bf16 v[114:117], v[178:181], v[154:157], v[114:117]
	v_add_f32_e32 v250, v98, v250
	s_add_u32 m0, s80, 49152
	s_nop 0
	global_load_lds_dwordx4 v248, s[100:101]
	v_mfma_f32_16x16x32_bf16 v[118:121], v[178:181], v[170:173], v[118:121]
	ds_read_b128 v[178:181], v237 offset:16384
	v_add_f32_e32 v250, v99, v250
	v_add_f32_e32 v250, v100, v250
	s_waitcnt lgkmcnt(3)
	v_mfma_f32_16x16x32_bf16 v[122:125], v[182:185], v[154:157], v[122:125]
	v_add_f32_e32 v250, v101, v250
	v_mfma_f32_16x16x32_bf16 v[126:129], v[182:185], v[170:173], v[126:129]
	ds_read_b128 v[182:185], v237 offset:20480
	v_add_f32_e32 v250, v106, v250
	v_add_f32_e32 v250, v107, v250
	s_waitcnt lgkmcnt(3)
	v_mfma_f32_16x16x32_bf16 v[130:133], v[186:189], v[154:157], v[130:133]
	v_add_f32_e32 v250, v108, v250
	ds_read_b64_tr_b16 v[202:203], v238 offset:0
	ds_read_b64_tr_b16 v[204:205], v238 offset:4096
	v_mfma_f32_16x16x32_bf16 v[134:137], v[186:189], v[170:173], v[134:137]
	ds_read_b128 v[186:189], v237 offset:24576
	v_add_f32_e32 v250, v109, v250
	v_cvt_pk_bf16_f32 v98, v98, v99
	s_waitcnt lgkmcnt(5)
	v_mfma_f32_16x16x32_bf16 v[138:141], v[190:193], v[154:157], v[138:141]
	v_cvt_pk_bf16_f32 v99, v100, v101
	ds_read_b64_tr_b16 v[206:207], v239 offset:0
	ds_read_b64_tr_b16 v[208:209], v239 offset:4096
	v_mfma_f32_16x16x32_bf16 v[142:145], v[190:193], v[170:173], v[142:145]
	ds_read_b128 v[190:193], v237 offset:28672
	v_cvt_pk_bf16_f32 v100, v106, v107
	v_cvt_pk_bf16_f32 v101, v108, v109
	s_waitcnt lgkmcnt(7)
	v_mfma_f32_16x16x32_bf16 v[114:117], v[178:181], v[158:161], v[114:117]
	v_add_f32_e32 v251, v102, v251
	s_add_u32 m0, s80, 50176
	s_nop 0
	global_load_lds_dwordx4 v249, s[100:101]
	ds_read_b64_tr_b16 v[210:211], v240 offset:0
	ds_read_b64_tr_b16 v[212:213], v240 offset:4096
	v_mfma_f32_16x16x32_bf16 v[118:121], v[178:181], v[174:177], v[118:121]
	v_add_f32_e32 v251, v103, v251
	v_add_f32_e32 v251, v104, v251
	s_waitcnt lgkmcnt(8)
	v_mfma_f32_16x16x32_bf16 v[122:125], v[182:185], v[158:161], v[122:125]
	v_add_f32_e32 v251, v105, v251
	ds_read_b64_tr_b16 v[214:215], v241 offset:0
	ds_read_b64_tr_b16 v[216:217], v241 offset:4096
	v_mfma_f32_16x16x32_bf16 v[126:129], v[182:185], v[174:177], v[126:129]
	v_add_f32_e32 v251, v110, v251
	v_add_f32_e32 v251, v111, v251
	s_waitcnt lgkmcnt(7)
	v_mfma_f32_16x16x32_bf16 v[130:133], v[186:189], v[158:161], v[130:133]
	v_add_f32_e32 v251, v112, v251
	ds_read_b64_tr_b16 v[218:219], v242 offset:0
	ds_read_b64_tr_b16 v[220:221], v242 offset:4096
	v_mfma_f32_16x16x32_bf16 v[134:137], v[186:189], v[174:177], v[134:137]
	v_add_f32_e32 v251, v113, v251
	v_cvt_pk_bf16_f32 v102, v102, v103
	s_waitcnt lgkmcnt(6)
; __device__ __forceinline__ void partialSM(f32x16& p0, f32x16& p1, float mC) {
;   (void)mC; (void)p1;
;   for (int r = 0; r < 16; ++r) p0[r] = __builtin_amdgcn_exp2f(p0[r]);
; }
; __device__ __forceinline__ void finishSM(f32x16& p0, f32x16& p1, float& l_reg, bf16x8& pa0, bf16x8& pa1, bf16x8& pa2, bf16x8& pa3) {
;   for (int r = 0; r < 16; ++r) p1[r] = __builtin_amdgcn_exp2f(p1[r]);
;   float ps = 0; for (int r = 0; r < 16; ++r) ps += p0[r]; for (int r = 0; r < 16; ++r) ps += p1[r];
;   { auto rr = __builtin_amdgcn_permlane32_swap(__float_as_uint(ps), __float_as_uint(ps), false, false);
;     ps = __uint_as_float(rr[0]) + __uint_as_float(rr[1]); }
;   l_reg += ps;
;     ...
;   PK4(p0, 0, pa0); PK4(p0, 8, pa1); PK4(p1, 0, pa2); PK4(p1, 8, pa3);
;     ...
; }
; __device__ __forceinline__ void qkt(f32x16& p0, f32x16& p1, const bf16* Ks, const bf16x8* qr, int r32, int hi, const f32x16& negm) {
; #pragma unroll
;   for (int d0 = 0; d0 < 8; ++d0) { int cb = (d0 * 16 + hi * 8) * 2;
;     bf16x8 b0 = *reinterpret_cast<const bf16x8*>((const char*)Ks + KSWZ(r32, cb));
;     bf16x8 b1 = *reinterpret_cast<const bf16x8*>((const char*)Ks + KSWZ(32 + r32, cb));
;     if (d0 == 0) { p0 = __builtin_amdgcn_mfma_f32_32x32x16_bf16(b0, qr[0], negm, 0, 0, 0); p1 = __builtin_amdgcn_mfma_f32_32x32x16_bf16(b1, qr[0], negm, 0, 0, 0); }
;     else { p0 = __builtin_amdgcn_mfma_f32_32x32x16_bf16(b0, qr[d0], p0, 0, 0, 0); p1 = __builtin_amdgcn_mfma_f32_32x32x16_bf16(b1, qr[d0], p1, 0, 0, 0); } }
; }
; __device__ __forceinline__ int v_st(int k, int c) { const int kk = (k & ~0xC) | ((k & 4) << 1) | ((k & 8) >> 1); return ((kk >> 3) * 4 + (c >> 5)) * 512 + ((kk & 7) * 32 + (c & 31)) * 2; }
; __device__ __forceinline__ int v_rd_base(int lane) { return ((lane & 3) << 3) | (((lane >> 2) & 3) << 6) | (((lane >> 4) & 1) << 5) | (((lane >> 5) & 1) << 8); }
; template <int OFF> __device__ __forceinline__ s16x4 tr_read(int vb) {
;   s16x4 r; asm volatile("ds_read_b64_tr_b16 %0, %1 offset:%2" : "=&v"(r) : "v"(vb), "i"(OFF) : "memory"); return r;
; }
; template <int D0> __device__ __forceinline__ void pv_one(f32x16& od, int vb, bf16x8 pa0, bf16x8 pa1, bf16x8 pa2, bf16x8 pa3) {
;   const s16x4 l0 = tr_read<v_rd_off(D0, 0, 0)>(vb), h0 = tr_read<v_rd_off(D0, 0, 1)>(vb), l1 = tr_read<v_rd_off(D0, 1, 0)>(vb), h1 = tr_read<v_rd_off(D0, 1, 1)>(vb);
	v_mfma_f32_16x16x32_bf16 v[138:141], v[190:193], v[158:161], v[138:141]
	v_cvt_pk_bf16_f32 v103, v104, v105
	ds_read_b64_tr_b16 v[222:223], v243 offset:0
	ds_read_b64_tr_b16 v[224:225], v243 offset:4096
	v_mfma_f32_16x16x32_bf16 v[142:145], v[190:193], v[174:177], v[142:145]
	v_cvt_pk_bf16_f32 v104, v110, v111
	v_cvt_pk_bf16_f32 v105, v112, v113
	v_mfma_f32_16x16x32_bf16 v[18:21], v[202:205], v[82:85], v[18:21]
	v_exp_f32_e32 v114, v114
	v_mfma_f32_16x16x32_bf16 v[22:25], v[202:205], v[86:89], v[22:25]
	ds_read_b64_tr_b16 v[202:203], v244 offset:0
	ds_read_b64_tr_b16 v[204:205], v244 offset:4096
	v_exp_f32_e32 v115, v115
	v_mfma_f32_16x16x32_bf16 v[26:29], v[206:209], v[82:85], v[26:29]
	v_exp_f32_e32 v116, v116
	v_mfma_f32_16x16x32_bf16 v[30:33], v[206:209], v[86:89], v[30:33]
	ds_read_b64_tr_b16 v[206:207], v245 offset:0
	ds_read_b64_tr_b16 v[208:209], v245 offset:4096
	v_exp_f32_e32 v117, v117
	s_waitcnt lgkmcnt(10)
	v_mfma_f32_16x16x32_bf16 v[34:37], v[210:213], v[82:85], v[34:37]
	v_exp_f32_e32 v118, v118
	v_mfma_f32_16x16x32_bf16 v[38:41], v[210:213], v[86:89], v[38:41]
	ds_read_b64_tr_b16 v[210:211], v238 offset:8192
	ds_read_b64_tr_b16 v[212:213], v238 offset:12288
	v_exp_f32_e32 v119, v119
	s_waitcnt lgkmcnt(10)
	v_mfma_f32_16x16x32_bf16 v[42:45], v[214:217], v[82:85], v[42:45]
	v_exp_f32_e32 v120, v120
	v_mfma_f32_16x16x32_bf16 v[46:49], v[214:217], v[86:89], v[46:49]
	ds_read_b64_tr_b16 v[214:215], v239 offset:8192
	ds_read_b64_tr_b16 v[216:217], v239 offset:12288
	v_exp_f32_e32 v121, v121
	s_waitcnt lgkmcnt(10)
	v_mfma_f32_16x16x32_bf16 v[50:53], v[218:221], v[82:85], v[50:53]
	v_exp_f32_e32 v122, v122
	v_mfma_f32_16x16x32_bf16 v[54:57], v[218:221], v[86:89], v[54:57]
	ds_read_b64_tr_b16 v[218:219], v240 offset:8192
	ds_read_b64_tr_b16 v[220:221], v240 offset:12288
	v_exp_f32_e32 v123, v123
	s_waitcnt lgkmcnt(10)
	v_mfma_f32_16x16x32_bf16 v[58:61], v[222:225], v[82:85], v[58:61]
	v_exp_f32_e32 v124, v124
	v_mfma_f32_16x16x32_bf16 v[62:65], v[222:225], v[86:89], v[62:65]
	ds_read_b64_tr_b16 v[222:223], v241 offset:8192
	ds_read_b64_tr_b16 v[224:225], v241 offset:12288
	v_exp_f32_e32 v125, v125
	s_waitcnt lgkmcnt(10)
	v_mfma_f32_16x16x32_bf16 v[66:69], v[202:205], v[82:85], v[66:69]
	v_exp_f32_e32 v126, v126
	v_mfma_f32_16x16x32_bf16 v[70:73], v[202:205], v[86:89], v[70:73]
	ds_read_b64_tr_b16 v[202:203], v242 offset:8192
	ds_read_b64_tr_b16 v[204:205], v242 offset:12288
	v_exp_f32_e32 v127, v127
	s_waitcnt lgkmcnt(10)
	v_mfma_f32_16x16x32_bf16 v[74:77], v[206:209], v[82:85], v[74:77]
	v_exp_f32_e32 v128, v128
	v_mfma_f32_16x16x32_bf16 v[78:81], v[206:209], v[86:89], v[78:81]
	ds_read_b64_tr_b16 v[206:207], v243 offset:8192
	ds_read_b64_tr_b16 v[208:209], v243 offset:12288
	v_exp_f32_e32 v129, v129
	s_waitcnt lgkmcnt(10)
	v_mfma_f32_16x16x32_bf16 v[18:21], v[210:213], v[98:101], v[18:21]
	v_exp_f32_e32 v130, v130
	v_mfma_f32_16x16x32_bf16 v[22:25], v[210:213], v[102:105], v[22:25]
	ds_read_b64_tr_b16 v[210:211], v244 offset:8192
	ds_read_b64_tr_b16 v[212:213], v244 offset:12288
	v_exp_f32_e32 v131, v131
	s_waitcnt lgkmcnt(10)
	v_mfma_f32_16x16x32_bf16 v[26:29], v[214:217], v[98:101], v[26:29]
	v_exp_f32_e32 v132, v132
	v_mfma_f32_16x16x32_bf16 v[30:33], v[214:217], v[102:105], v[30:33]
	ds_read_b64_tr_b16 v[214:215], v245 offset:8192
	ds_read_b64_tr_b16 v[216:217], v245 offset:12288
	v_exp_f32_e32 v133, v133
	s_waitcnt lgkmcnt(10)
	v_mfma_f32_16x16x32_bf16 v[34:37], v[218:221], v[98:101], v[34:37]
	v_exp_f32_e32 v134, v134
	v_mfma_f32_16x16x32_bf16 v[38:41], v[218:221], v[102:105], v[38:41]
	v_exp_f32_e32 v135, v135
	s_waitcnt lgkmcnt(8)
	v_mfma_f32_16x16x32_bf16 v[42:45], v[222:225], v[98:101], v[42:45]
	v_exp_f32_e32 v136, v136
	v_mfma_f32_16x16x32_bf16 v[46:49], v[222:225], v[102:105], v[46:49]
	v_exp_f32_e32 v137, v137
	s_waitcnt lgkmcnt(6)
	v_mfma_f32_16x16x32_bf16 v[50:53], v[202:205], v[98:101], v[50:53]
	v_exp_f32_e32 v138, v138
	ds_read_b128 v[178:181], v234 offset:32768
	v_mfma_f32_16x16x32_bf16 v[54:57], v[202:205], v[102:105], v[54:57]
	v_exp_f32_e32 v139, v139
	s_waitcnt lgkmcnt(5)
	v_mfma_f32_16x16x32_bf16 v[58:61], v[206:209], v[98:101], v[58:61]
	v_exp_f32_e32 v140, v140
	ds_read_b128 v[182:185], v234 offset:36864
	v_mfma_f32_16x16x32_bf16 v[62:65], v[206:209], v[102:105], v[62:65]
	v_exp_f32_e32 v141, v141
	s_waitcnt lgkmcnt(4)
	v_mfma_f32_16x16x32_bf16 v[66:69], v[210:213], v[98:101], v[66:69]
	v_exp_f32_e32 v142, v142
	ds_read_b128 v[186:189], v234 offset:40960
	v_mfma_f32_16x16x32_bf16 v[70:73], v[210:213], v[102:105], v[70:73]
	v_exp_f32_e32 v143, v143
	s_waitcnt lgkmcnt(3)
	v_mfma_f32_16x16x32_bf16 v[74:77], v[214:217], v[98:101], v[74:77]
	v_exp_f32_e32 v144, v144
	ds_read_b128 v[190:193], v234 offset:45056
	v_mfma_f32_16x16x32_bf16 v[78:81], v[214:217], v[102:105], v[78:81]
	v_exp_f32_e32 v145, v145
	s_waitcnt vmcnt(4)
	s_barrier
; __device__ __forceinline__ void partialSM(f32x16& p0, f32x16& p1, float mC) {
;   (void)mC; (void)p1;
;   for (int r = 0; r < 16; ++r) p0[r] = __builtin_amdgcn_exp2f(p0[r]);
; }
; __device__ __forceinline__ void finishSM(f32x16& p0, f32x16& p1, float& l_reg, bf16x8& pa0, bf16x8& pa1, bf16x8& pa2, bf16x8& pa3) {
;   for (int r = 0; r < 16; ++r) p1[r] = __builtin_amdgcn_exp2f(p1[r]);
;   float ps = 0; for (int r = 0; r < 16; ++r) ps += p0[r]; for (int r = 0; r < 16; ++r) ps += p1[r];
;   { auto rr = __builtin_amdgcn_permlane32_swap(__float_as_uint(ps), __float_as_uint(ps), false, false);
;     ps = __uint_as_float(rr[0]) + __uint_as_float(rr[1]); }
;   l_reg += ps;
;     ...
;   PK4(p0, 0, pa0); PK4(p0, 8, pa1); PK4(p1, 0, pa2); PK4(p1, 8, pa3);
;     ...
; }
; __device__ __forceinline__ void qkt(f32x16& p0, f32x16& p1, const bf16* Ks, const bf16x8* qr, int r32, int hi, const f32x16& negm) {
; #pragma unroll
;   for (int d0 = 0; d0 < 8; ++d0) { int cb = (d0 * 16 + hi * 8) * 2;
;     bf16x8 b0 = *reinterpret_cast<const bf16x8*>((const char*)Ks + KSWZ(r32, cb));
;     bf16x8 b1 = *reinterpret_cast<const bf16x8*>((const char*)Ks + KSWZ(32 + r32, cb));
;     if (d0 == 0) { p0 = __builtin_amdgcn_mfma_f32_32x32x16_bf16(b0, qr[0], negm, 0, 0, 0); p1 = __builtin_amdgcn_mfma_f32_32x32x16_bf16(b1, qr[0], negm, 0, 0, 0); }
;     else { p0 = __builtin_amdgcn_mfma_f32_32x32x16_bf16(b0, qr[d0], p0, 0, 0, 0); p1 = __builtin_amdgcn_mfma_f32_32x32x16_bf16(b1, qr[d0], p1, 0, 0, 0); } }
; }
; __device__ __forceinline__ int v_st(int k, int c) { const int kk = (k & ~0xC) | ((k & 4) << 1) | ((k & 8) >> 1); return ((kk >> 3) * 4 + (c >> 5)) * 512 + ((kk & 7) * 32 + (c & 31)) * 2; }
; __device__ __forceinline__ int v_rd_base(int lane) { return ((lane & 3) << 3) | (((lane >> 2) & 3) << 6) | (((lane >> 4) & 1) << 5) | (((lane >> 5) & 1) << 8); }
; template <int OFF> __device__ __forceinline__ s16x4 tr_read(int vb) {
;   s16x4 r; asm volatile("ds_read_b64_tr_b16 %0, %1 offset:%2" : "=&v"(r) : "v"(vb), "i"(OFF) : "memory"); return r;
; }
; template <int D0> __device__ __forceinline__ void pv_one(f32x16& od, int vb, bf16x8 pa0, bf16x8 pa1, bf16x8 pa2, bf16x8 pa3) {
;   const s16x4 l0 = tr_read<v_rd_off(D0, 0, 0)>(vb), h0 = tr_read<v_rd_off(D0, 0, 1)>(vb), l1 = tr_read<v_rd_off(D0, 1, 0)>(vb), h1 = tr_read<v_rd_off(D0, 1, 1)>(vb);
	s_waitcnt lgkmcnt(3)
	v_mfma_f32_16x16x32_bf16 v[82:85], v[178:181], v[146:149], v[2:5]
	v_add_f32_e32 v250, v114, v250
	s_add_u32 s98, s98, 0x8000
	s_addc_u32 s99, s99, 0
	s_add_u32 s100, s100, 0x8000
	s_addc_u32 s101, s101, 0
	s_add_u32 m0, s79, 16384
	s_nop 0
	global_load_lds_dwordx4 v246, s[98:99]
	v_mfma_f32_16x16x32_bf16 v[86:89], v[178:181], v[162:165], v[2:5]
	ds_read_b128 v[178:181], v235 offset:32768
	v_add_f32_e32 v250, v115, v250
	v_add_f32_e32 v250, v116, v250
	s_waitcnt lgkmcnt(3)
	v_mfma_f32_16x16x32_bf16 v[90:93], v[182:185], v[146:149], v[2:5]
	v_add_f32_e32 v250, v117, v250
	v_mfma_f32_16x16x32_bf16 v[94:97], v[182:185], v[162:165], v[2:5]
	ds_read_b128 v[182:185], v235 offset:36864
	v_add_f32_e32 v250, v122, v250
	v_add_f32_e32 v250, v123, v250
	s_waitcnt lgkmcnt(3)
	v_mfma_f32_16x16x32_bf16 v[98:101], v[186:189], v[146:149], v[2:5]
	v_add_f32_e32 v250, v124, v250
	v_mfma_f32_16x16x32_bf16 v[102:105], v[186:189], v[162:165], v[2:5]
	ds_read_b128 v[186:189], v235 offset:40960
	v_add_f32_e32 v250, v125, v250
	v_cvt_pk_bf16_f32 v114, v114, v115
	s_waitcnt lgkmcnt(3)
	v_mfma_f32_16x16x32_bf16 v[106:109], v[190:193], v[146:149], v[2:5]
	v_cvt_pk_bf16_f32 v115, v116, v117
	v_mfma_f32_16x16x32_bf16 v[110:113], v[190:193], v[162:165], v[2:5]
	ds_read_b128 v[190:193], v235 offset:45056
	v_cvt_pk_bf16_f32 v116, v122, v123
	v_cvt_pk_bf16_f32 v117, v124, v125
	s_waitcnt lgkmcnt(3)
	v_mfma_f32_16x16x32_bf16 v[82:85], v[178:181], v[150:153], v[82:85]
	v_add_f32_e32 v251, v118, v251
	s_add_u32 m0, s79, 17408
	s_nop 0
	global_load_lds_dwordx4 v247, s[98:99]
	v_mfma_f32_16x16x32_bf16 v[86:89], v[178:181], v[166:169], v[86:89]
	ds_read_b128 v[178:181], v236 offset:32768
	v_add_f32_e32 v251, v119, v251
	v_add_f32_e32 v251, v120, v251
	s_waitcnt lgkmcnt(3)
	v_mfma_f32_16x16x32_bf16 v[90:93], v[182:185], v[150:153], v[90:93]
	v_add_f32_e32 v251, v121, v251
	v_mfma_f32_16x16x32_bf16 v[94:97], v[182:185], v[166:169], v[94:97]
	ds_read_b128 v[182:185], v236 offset:36864
	v_add_f32_e32 v251, v126, v251
	v_add_f32_e32 v251, v127, v251
	s_waitcnt lgkmcnt(3)
	v_mfma_f32_16x16x32_bf16 v[98:101], v[186:189], v[150:153], v[98:101]
	v_add_f32_e32 v251, v128, v251
	v_mfma_f32_16x16x32_bf16 v[102:105], v[186:189], v[166:169], v[102:105]
	ds_read_b128 v[186:189], v236 offset:40960
	v_add_f32_e32 v251, v129, v251
	v_cvt_pk_bf16_f32 v118, v118, v119
	s_waitcnt lgkmcnt(3)
	v_mfma_f32_16x16x32_bf16 v[106:109], v[190:193], v[150:153], v[106:109]
	v_cvt_pk_bf16_f32 v119, v120, v121
	v_mfma_f32_16x16x32_bf16 v[110:113], v[190:193], v[166:169], v[110:113]
	ds_read_b128 v[190:193], v236 offset:45056
	v_cvt_pk_bf16_f32 v120, v126, v127
	v_cvt_pk_bf16_f32 v121, v128, v129
	s_waitcnt lgkmcnt(3)
	v_mfma_f32_16x16x32_bf16 v[82:85], v[178:181], v[154:157], v[82:85]
	v_add_f32_e32 v250, v130, v250
	s_add_u32 m0, s80, 0
	s_nop 0
	global_load_lds_dwordx4 v248, s[100:101]
	v_mfma_f32_16x16x32_bf16 v[86:89], v[178:181], v[170:173], v[86:89]
	ds_read_b128 v[178:181], v237 offset:32768
	v_add_f32_e32 v250, v131, v250
	v_add_f32_e32 v250, v132, v250
	s_waitcnt lgkmcnt(3)
	v_mfma_f32_16x16x32_bf16 v[90:93], v[182:185], v[154:157], v[90:93]
	v_add_f32_e32 v250, v133, v250
	v_mfma_f32_16x16x32_bf16 v[94:97], v[182:185], v[170:173], v[94:97]
	ds_read_b128 v[182:185], v237 offset:36864
	v_add_f32_e32 v250, v138, v250
	v_add_f32_e32 v250, v139, v250
	s_waitcnt lgkmcnt(3)
	v_mfma_f32_16x16x32_bf16 v[98:101], v[186:189], v[154:157], v[98:101]
	v_add_f32_e32 v250, v140, v250
	ds_read_b64_tr_b16 v[202:203], v238 offset:16384
	ds_read_b64_tr_b16 v[204:205], v238 offset:20480
	v_mfma_f32_16x16x32_bf16 v[102:105], v[186:189], v[170:173], v[102:105]
	ds_read_b128 v[186:189], v237 offset:40960
	v_add_f32_e32 v250, v141, v250
	v_cvt_pk_bf16_f32 v130, v130, v131
	s_waitcnt lgkmcnt(5)
	v_mfma_f32_16x16x32_bf16 v[106:109], v[190:193], v[154:157], v[106:109]
	v_cvt_pk_bf16_f32 v131, v132, v133
	ds_read_b64_tr_b16 v[206:207], v239 offset:16384
	ds_read_b64_tr_b16 v[208:209], v239 offset:20480
	v_mfma_f32_16x16x32_bf16 v[110:113], v[190:193], v[170:173], v[110:113]
	ds_read_b128 v[190:193], v237 offset:45056
	v_cvt_pk_bf16_f32 v132, v138, v139
	v_cvt_pk_bf16_f32 v133, v140, v141
	s_waitcnt lgkmcnt(7)
	v_mfma_f32_16x16x32_bf16 v[82:85], v[178:181], v[158:161], v[82:85]
	v_add_f32_e32 v251, v134, v251
	s_add_u32 m0, s80, 1024
	s_nop 0
	global_load_lds_dwordx4 v249, s[100:101]
	ds_read_b64_tr_b16 v[210:211], v240 offset:16384
	ds_read_b64_tr_b16 v[212:213], v240 offset:20480
	v_mfma_f32_16x16x32_bf16 v[86:89], v[178:181], v[174:177], v[86:89]
	v_add_f32_e32 v251, v135, v251
	v_add_f32_e32 v251, v136, v251
	s_waitcnt lgkmcnt(8)
	v_mfma_f32_16x16x32_bf16 v[90:93], v[182:185], v[158:161], v[90:93]
	v_add_f32_e32 v251, v137, v251
	ds_read_b64_tr_b16 v[214:215], v241 offset:16384
	ds_read_b64_tr_b16 v[216:217], v241 offset:20480
	v_mfma_f32_16x16x32_bf16 v[94:97], v[182:185], v[174:177], v[94:97]
	v_add_f32_e32 v251, v142, v251
	v_add_f32_e32 v251, v143, v251
	s_waitcnt lgkmcnt(7)
	v_mfma_f32_16x16x32_bf16 v[98:101], v[186:189], v[158:161], v[98:101]
	v_add_f32_e32 v251, v144, v251
	ds_read_b64_tr_b16 v[218:219], v242 offset:16384
	ds_read_b64_tr_b16 v[220:221], v242 offset:20480
	v_mfma_f32_16x16x32_bf16 v[102:105], v[186:189], v[174:177], v[102:105]
	v_add_f32_e32 v251, v145, v251
	v_cvt_pk_bf16_f32 v134, v134, v135
	s_waitcnt lgkmcnt(6)
; __device__ __forceinline__ void partialSM(f32x16& p0, f32x16& p1, float mC) {
;   (void)mC; (void)p1;
;   for (int r = 0; r < 16; ++r) p0[r] = __builtin_amdgcn_exp2f(p0[r]);
; }
; __device__ __forceinline__ void finishSM(f32x16& p0, f32x16& p1, float& l_reg, bf16x8& pa0, bf16x8& pa1, bf16x8& pa2, bf16x8& pa3) {
;   for (int r = 0; r < 16; ++r) p1[r] = __builtin_amdgcn_exp2f(p1[r]);
;   float ps = 0; for (int r = 0; r < 16; ++r) ps += p0[r]; for (int r = 0; r < 16; ++r) ps += p1[r];
;   { auto rr = __builtin_amdgcn_permlane32_swap(__float_as_uint(ps), __float_as_uint(ps), false, false);
;     ps = __uint_as_float(rr[0]) + __uint_as_float(rr[1]); }
;   l_reg += ps;
;     ...
;   PK4(p0, 0, pa0); PK4(p0, 8, pa1); PK4(p1, 0, pa2); PK4(p1, 8, pa3);
;     ...
; }
; __device__ __forceinline__ void qkt(f32x16& p0, f32x16& p1, const bf16* Ks, const bf16x8* qr, int r32, int hi, const f32x16& negm) {
; #pragma unroll
;   for (int d0 = 0; d0 < 8; ++d0) { int cb = (d0 * 16 + hi * 8) * 2;
;     bf16x8 b0 = *reinterpret_cast<const bf16x8*>((const char*)Ks + KSWZ(r32, cb));
;     bf16x8 b1 = *reinterpret_cast<const bf16x8*>((const char*)Ks + KSWZ(32 + r32, cb));
;     if (d0 == 0) { p0 = __builtin_amdgcn_mfma_f32_32x32x16_bf16(b0, qr[0], negm, 0, 0, 0); p1 = __builtin_amdgcn_mfma_f32_32x32x16_bf16(b1, qr[0], negm, 0, 0, 0); }
;     else { p0 = __builtin_amdgcn_mfma_f32_32x32x16_bf16(b0, qr[d0], p0, 0, 0, 0); p1 = __builtin_amdgcn_mfma_f32_32x32x16_bf16(b1, qr[d0], p1, 0, 0, 0); } }
; }
; __device__ __forceinline__ int v_st(int k, int c) { const int kk = (k & ~0xC) | ((k & 4) << 1) | ((k & 8) >> 1); return ((kk >> 3) * 4 + (c >> 5)) * 512 + ((kk & 7) * 32 + (c & 31)) * 2; }
; __device__ __forceinline__ int v_rd_base(int lane) { return ((lane & 3) << 3) | (((lane >> 2) & 3) << 6) | (((lane >> 4) & 1) << 5) | (((lane >> 5) & 1) << 8); }
; template <int OFF> __device__ __forceinline__ s16x4 tr_read(int vb) {
;   s16x4 r; asm volatile("ds_read_b64_tr_b16 %0, %1 offset:%2" : "=&v"(r) : "v"(vb), "i"(OFF) : "memory"); return r;
; }
; template <int D0> __device__ __forceinline__ void pv_one(f32x16& od, int vb, bf16x8 pa0, bf16x8 pa1, bf16x8 pa2, bf16x8 pa3) {
;   const s16x4 l0 = tr_read<v_rd_off(D0, 0, 0)>(vb), h0 = tr_read<v_rd_off(D0, 0, 1)>(vb), l1 = tr_read<v_rd_off(D0, 1, 0)>(vb), h1 = tr_read<v_rd_off(D0, 1, 1)>(vb);
	v_mfma_f32_16x16x32_bf16 v[106:109], v[190:193], v[158:161], v[106:109]
	v_cvt_pk_bf16_f32 v135, v136, v137
	ds_read_b64_tr_b16 v[222:223], v243 offset:16384
	ds_read_b64_tr_b16 v[224:225], v243 offset:20480
	v_mfma_f32_16x16x32_bf16 v[110:113], v[190:193], v[174:177], v[110:113]
	v_cvt_pk_bf16_f32 v136, v142, v143
	v_cvt_pk_bf16_f32 v137, v144, v145
	v_mfma_f32_16x16x32_bf16 v[18:21], v[202:205], v[114:117], v[18:21]
	v_exp_f32_e32 v82, v82
	v_mfma_f32_16x16x32_bf16 v[22:25], v[202:205], v[118:121], v[22:25]
	ds_read_b64_tr_b16 v[202:203], v244 offset:16384
	ds_read_b64_tr_b16 v[204:205], v244 offset:20480
	v_exp_f32_e32 v83, v83
	v_mfma_f32_16x16x32_bf16 v[26:29], v[206:209], v[114:117], v[26:29]
	v_exp_f32_e32 v84, v84
	v_mfma_f32_16x16x32_bf16 v[30:33], v[206:209], v[118:121], v[30:33]
	ds_read_b64_tr_b16 v[206:207], v245 offset:16384
	ds_read_b64_tr_b16 v[208:209], v245 offset:20480
	v_exp_f32_e32 v85, v85
	s_waitcnt lgkmcnt(10)
	v_mfma_f32_16x16x32_bf16 v[34:37], v[210:213], v[114:117], v[34:37]
	v_exp_f32_e32 v86, v86
	v_mfma_f32_16x16x32_bf16 v[38:41], v[210:213], v[118:121], v[38:41]
	ds_read_b64_tr_b16 v[210:211], v238 offset:24576
	ds_read_b64_tr_b16 v[212:213], v238 offset:28672
	v_exp_f32_e32 v87, v87
	s_waitcnt lgkmcnt(10)
	v_mfma_f32_16x16x32_bf16 v[42:45], v[214:217], v[114:117], v[42:45]
	v_exp_f32_e32 v88, v88
	v_mfma_f32_16x16x32_bf16 v[46:49], v[214:217], v[118:121], v[46:49]
	ds_read_b64_tr_b16 v[214:215], v239 offset:24576
	ds_read_b64_tr_b16 v[216:217], v239 offset:28672
	v_exp_f32_e32 v89, v89
	s_waitcnt lgkmcnt(10)
	v_mfma_f32_16x16x32_bf16 v[50:53], v[218:221], v[114:117], v[50:53]
	v_exp_f32_e32 v90, v90
	v_mfma_f32_16x16x32_bf16 v[54:57], v[218:221], v[118:121], v[54:57]
	ds_read_b64_tr_b16 v[218:219], v240 offset:24576
	ds_read_b64_tr_b16 v[220:221], v240 offset:28672
	v_exp_f32_e32 v91, v91
	s_waitcnt lgkmcnt(10)
	v_mfma_f32_16x16x32_bf16 v[58:61], v[222:225], v[114:117], v[58:61]
	v_exp_f32_e32 v92, v92
	v_mfma_f32_16x16x32_bf16 v[62:65], v[222:225], v[118:121], v[62:65]
	ds_read_b64_tr_b16 v[222:223], v241 offset:24576
	ds_read_b64_tr_b16 v[224:225], v241 offset:28672
	v_exp_f32_e32 v93, v93
	s_waitcnt lgkmcnt(10)
	v_mfma_f32_16x16x32_bf16 v[66:69], v[202:205], v[114:117], v[66:69]
	v_exp_f32_e32 v94, v94
	v_mfma_f32_16x16x32_bf16 v[70:73], v[202:205], v[118:121], v[70:73]
	ds_read_b64_tr_b16 v[202:203], v242 offset:24576
	ds_read_b64_tr_b16 v[204:205], v242 offset:28672
	v_exp_f32_e32 v95, v95
	s_waitcnt lgkmcnt(10)
	v_mfma_f32_16x16x32_bf16 v[74:77], v[206:209], v[114:117], v[74:77]
	v_exp_f32_e32 v96, v96
	v_mfma_f32_16x16x32_bf16 v[78:81], v[206:209], v[118:121], v[78:81]
	ds_read_b64_tr_b16 v[206:207], v243 offset:24576
	ds_read_b64_tr_b16 v[208:209], v243 offset:28672
	v_exp_f32_e32 v97, v97
	s_waitcnt lgkmcnt(10)
	v_mfma_f32_16x16x32_bf16 v[18:21], v[210:213], v[130:133], v[18:21]
	v_exp_f32_e32 v98, v98
	v_mfma_f32_16x16x32_bf16 v[22:25], v[210:213], v[134:137], v[22:25]
	ds_read_b64_tr_b16 v[210:211], v244 offset:24576
	ds_read_b64_tr_b16 v[212:213], v244 offset:28672
	v_exp_f32_e32 v99, v99
	s_waitcnt lgkmcnt(10)
	v_mfma_f32_16x16x32_bf16 v[26:29], v[214:217], v[130:133], v[26:29]
	v_exp_f32_e32 v100, v100
	v_mfma_f32_16x16x32_bf16 v[30:33], v[214:217], v[134:137], v[30:33]
	ds_read_b64_tr_b16 v[214:215], v245 offset:24576
	ds_read_b64_tr_b16 v[216:217], v245 offset:28672
	v_exp_f32_e32 v101, v101
	s_waitcnt lgkmcnt(10)
	v_mfma_f32_16x16x32_bf16 v[34:37], v[218:221], v[130:133], v[34:37]
	v_exp_f32_e32 v102, v102
	v_mfma_f32_16x16x32_bf16 v[38:41], v[218:221], v[134:137], v[38:41]
	v_exp_f32_e32 v103, v103
	s_waitcnt lgkmcnt(8)
	v_mfma_f32_16x16x32_bf16 v[42:45], v[222:225], v[130:133], v[42:45]
	v_exp_f32_e32 v104, v104
	v_mfma_f32_16x16x32_bf16 v[46:49], v[222:225], v[134:137], v[46:49]
	v_exp_f32_e32 v105, v105
	s_waitcnt lgkmcnt(6)
	v_mfma_f32_16x16x32_bf16 v[50:53], v[202:205], v[130:133], v[50:53]
	v_exp_f32_e32 v106, v106
	ds_read_b128 v[178:181], v234 offset:49152
	v_mfma_f32_16x16x32_bf16 v[54:57], v[202:205], v[134:137], v[54:57]
	v_exp_f32_e32 v107, v107
	s_waitcnt lgkmcnt(5)
	v_mfma_f32_16x16x32_bf16 v[58:61], v[206:209], v[130:133], v[58:61]
	v_exp_f32_e32 v108, v108
	ds_read_b128 v[182:185], v234 offset:53248
	v_mfma_f32_16x16x32_bf16 v[62:65], v[206:209], v[134:137], v[62:65]
	v_exp_f32_e32 v109, v109
	s_waitcnt lgkmcnt(4)
	v_mfma_f32_16x16x32_bf16 v[66:69], v[210:213], v[130:133], v[66:69]
	v_exp_f32_e32 v110, v110
	ds_read_b128 v[186:189], v234 offset:57344
	v_mfma_f32_16x16x32_bf16 v[70:73], v[210:213], v[134:137], v[70:73]
	v_exp_f32_e32 v111, v111
	s_waitcnt lgkmcnt(3)
	v_mfma_f32_16x16x32_bf16 v[74:77], v[214:217], v[130:133], v[74:77]
	v_exp_f32_e32 v112, v112
	ds_read_b128 v[190:193], v234 offset:61440
	v_mfma_f32_16x16x32_bf16 v[78:81], v[214:217], v[134:137], v[78:81]
	v_exp_f32_e32 v113, v113
	s_waitcnt vmcnt(4)
	s_barrier
; __device__ __forceinline__ void partialSM(f32x16& p0, f32x16& p1, float mC) {
;   (void)mC; (void)p1;
;   for (int r = 0; r < 16; ++r) p0[r] = __builtin_amdgcn_exp2f(p0[r]);
; }
; __device__ __forceinline__ void finishSM(f32x16& p0, f32x16& p1, float& l_reg, bf16x8& pa0, bf16x8& pa1, bf16x8& pa2, bf16x8& pa3) {
;   for (int r = 0; r < 16; ++r) p1[r] = __builtin_amdgcn_exp2f(p1[r]);
;   float ps = 0; for (int r = 0; r < 16; ++r) ps += p0[r]; for (int r = 0; r < 16; ++r) ps += p1[r];
;   { auto rr = __builtin_amdgcn_permlane32_swap(__float_as_uint(ps), __float_as_uint(ps), false, false);
;     ps = __uint_as_float(rr[0]) + __uint_as_float(rr[1]); }
;   l_reg += ps;
;     ...
;   PK4(p0, 0, pa0); PK4(p0, 8, pa1); PK4(p1, 0, pa2); PK4(p1, 8, pa3);
;     ...
; }
; __device__ __forceinline__ void qkt(f32x16& p0, f32x16& p1, const bf16* Ks, const bf16x8* qr, int r32, int hi, const f32x16& negm) {
; #pragma unroll
;   for (int d0 = 0; d0 < 8; ++d0) { int cb = (d0 * 16 + hi * 8) * 2;
;     bf16x8 b0 = *reinterpret_cast<const bf16x8*>((const char*)Ks + KSWZ(r32, cb));
;     bf16x8 b1 = *reinterpret_cast<const bf16x8*>((const char*)Ks + KSWZ(32 + r32, cb));
;     if (d0 == 0) { p0 = __builtin_amdgcn_mfma_f32_32x32x16_bf16(b0, qr[0], negm, 0, 0, 0); p1 = __builtin_amdgcn_mfma_f32_32x32x16_bf16(b1, qr[0], negm, 0, 0, 0); }
;     else { p0 = __builtin_amdgcn_mfma_f32_32x32x16_bf16(b0, qr[d0], p0, 0, 0, 0); p1 = __builtin_amdgcn_mfma_f32_32x32x16_bf16(b1, qr[d0], p1, 0, 0, 0); } }
; }
; __device__ __forceinline__ int v_st(int k, int c) { const int kk = (k & ~0xC) | ((k & 4) << 1) | ((k & 8) >> 1); return ((kk >> 3) * 4 + (c >> 5)) * 512 + ((kk & 7) * 32 + (c & 31)) * 2; }
; __device__ __forceinline__ int v_rd_base(int lane) { return ((lane & 3) << 3) | (((lane >> 2) & 3) << 6) | (((lane >> 4) & 1) << 5) | (((lane >> 5) & 1) << 8); }
; template <int OFF> __device__ __forceinline__ s16x4 tr_read(int vb) {
;   s16x4 r; asm volatile("ds_read_b64_tr_b16 %0, %1 offset:%2" : "=&v"(r) : "v"(vb), "i"(OFF) : "memory"); return r;
; }
; template <int D0> __device__ __forceinline__ void pv_one(f32x16& od, int vb, bf16x8 pa0, bf16x8 pa1, bf16x8 pa2, bf16x8 pa3) {
;   const s16x4 l0 = tr_read<v_rd_off(D0, 0, 0)>(vb), h0 = tr_read<v_rd_off(D0, 0, 1)>(vb), l1 = tr_read<v_rd_off(D0, 1, 0)>(vb), h1 = tr_read<v_rd_off(D0, 1, 1)>(vb);
	s_waitcnt lgkmcnt(3)
	v_mfma_f32_16x16x32_bf16 v[114:117], v[178:181], v[146:149], v[2:5]
	v_add_f32_e32 v250, v82, v250
	s_add_u32 s98, s98, 0x8000
	s_addc_u32 s99, s99, 0
	s_add_u32 s100, s100, 0x8000
	s_addc_u32 s101, s101, 0
	s_add_u32 m0, s79, 32768
	s_nop 0
	global_load_lds_dwordx4 v246, s[98:99]
	v_mfma_f32_16x16x32_bf16 v[118:121], v[178:181], v[162:165], v[2:5]
	ds_read_b128 v[178:181], v235 offset:49152
	v_add_f32_e32 v250, v83, v250
	v_add_f32_e32 v250, v84, v250
	s_waitcnt lgkmcnt(3)
	v_mfma_f32_16x16x32_bf16 v[122:125], v[182:185], v[146:149], v[2:5]
	v_add_f32_e32 v250, v85, v250
	v_mfma_f32_16x16x32_bf16 v[126:129], v[182:185], v[162:165], v[2:5]
	ds_read_b128 v[182:185], v235 offset:53248
	v_add_f32_e32 v250, v90, v250
	v_add_f32_e32 v250, v91, v250
	s_waitcnt lgkmcnt(3)
	v_mfma_f32_16x16x32_bf16 v[130:133], v[186:189], v[146:149], v[2:5]
	v_add_f32_e32 v250, v92, v250
	v_mfma_f32_16x16x32_bf16 v[134:137], v[186:189], v[162:165], v[2:5]
	ds_read_b128 v[186:189], v235 offset:57344
	v_add_f32_e32 v250, v93, v250
	v_cvt_pk_bf16_f32 v82, v82, v83
	s_waitcnt lgkmcnt(3)
	v_mfma_f32_16x16x32_bf16 v[138:141], v[190:193], v[146:149], v[2:5]
	v_cvt_pk_bf16_f32 v83, v84, v85
	v_mfma_f32_16x16x32_bf16 v[142:145], v[190:193], v[162:165], v[2:5]
	ds_read_b128 v[190:193], v235 offset:61440
	v_cvt_pk_bf16_f32 v84, v90, v91
	v_cvt_pk_bf16_f32 v85, v92, v93
	s_waitcnt lgkmcnt(3)
	v_mfma_f32_16x16x32_bf16 v[114:117], v[178:181], v[150:153], v[114:117]
	v_add_f32_e32 v251, v86, v251
	s_add_u32 m0, s79, 33792
	s_nop 0
	global_load_lds_dwordx4 v247, s[98:99]
	v_mfma_f32_16x16x32_bf16 v[118:121], v[178:181], v[166:169], v[118:121]
	ds_read_b128 v[178:181], v236 offset:49152
	v_add_f32_e32 v251, v87, v251
	v_add_f32_e32 v251, v88, v251
	s_waitcnt lgkmcnt(3)
	v_mfma_f32_16x16x32_bf16 v[122:125], v[182:185], v[150:153], v[122:125]
	v_add_f32_e32 v251, v89, v251
	v_mfma_f32_16x16x32_bf16 v[126:129], v[182:185], v[166:169], v[126:129]
	ds_read_b128 v[182:185], v236 offset:53248
	v_add_f32_e32 v251, v94, v251
	v_add_f32_e32 v251, v95, v251
	s_waitcnt lgkmcnt(3)
	v_mfma_f32_16x16x32_bf16 v[130:133], v[186:189], v[150:153], v[130:133]
	v_add_f32_e32 v251, v96, v251
	v_mfma_f32_16x16x32_bf16 v[134:137], v[186:189], v[166:169], v[134:137]
	ds_read_b128 v[186:189], v236 offset:57344
	v_add_f32_e32 v251, v97, v251
	v_cvt_pk_bf16_f32 v86, v86, v87
	s_waitcnt lgkmcnt(3)
	v_mfma_f32_16x16x32_bf16 v[138:141], v[190:193], v[150:153], v[138:141]
	v_cvt_pk_bf16_f32 v87, v88, v89
	v_mfma_f32_16x16x32_bf16 v[142:145], v[190:193], v[166:169], v[142:145]
	ds_read_b128 v[190:193], v236 offset:61440
	v_cvt_pk_bf16_f32 v88, v94, v95
	v_cvt_pk_bf16_f32 v89, v96, v97
	s_waitcnt lgkmcnt(3)
	v_mfma_f32_16x16x32_bf16 v[114:117], v[178:181], v[154:157], v[114:117]
	v_add_f32_e32 v250, v98, v250
	s_add_u32 m0, s80, 16384
	s_nop 0
	global_load_lds_dwordx4 v248, s[100:101]
	v_mfma_f32_16x16x32_bf16 v[118:121], v[178:181], v[170:173], v[118:121]
	ds_read_b128 v[178:181], v237 offset:49152
	v_add_f32_e32 v250, v99, v250
	v_add_f32_e32 v250, v100, v250
	s_waitcnt lgkmcnt(3)
	v_mfma_f32_16x16x32_bf16 v[122:125], v[182:185], v[154:157], v[122:125]
	v_add_f32_e32 v250, v101, v250
	v_mfma_f32_16x16x32_bf16 v[126:129], v[182:185], v[170:173], v[126:129]
	ds_read_b128 v[182:185], v237 offset:53248
	v_add_f32_e32 v250, v106, v250
	v_add_f32_e32 v250, v107, v250
	s_waitcnt lgkmcnt(3)
	v_mfma_f32_16x16x32_bf16 v[130:133], v[186:189], v[154:157], v[130:133]
	v_add_f32_e32 v250, v108, v250
	ds_read_b64_tr_b16 v[202:203], v238 offset:32768
	ds_read_b64_tr_b16 v[204:205], v238 offset:36864
	v_mfma_f32_16x16x32_bf16 v[134:137], v[186:189], v[170:173], v[134:137]
	ds_read_b128 v[186:189], v237 offset:57344
	v_add_f32_e32 v250, v109, v250
	v_cvt_pk_bf16_f32 v98, v98, v99
	s_waitcnt lgkmcnt(5)
	v_mfma_f32_16x16x32_bf16 v[138:141], v[190:193], v[154:157], v[138:141]
	v_cvt_pk_bf16_f32 v99, v100, v101
	ds_read_b64_tr_b16 v[206:207], v239 offset:32768
	ds_read_b64_tr_b16 v[208:209], v239 offset:36864
	v_mfma_f32_16x16x32_bf16 v[142:145], v[190:193], v[170:173], v[142:145]
	ds_read_b128 v[190:193], v237 offset:61440
	v_cvt_pk_bf16_f32 v100, v106, v107
	v_cvt_pk_bf16_f32 v101, v108, v109
	s_waitcnt lgkmcnt(7)
	v_mfma_f32_16x16x32_bf16 v[114:117], v[178:181], v[158:161], v[114:117]
	v_add_f32_e32 v251, v102, v251
	s_add_u32 m0, s80, 17408
	s_nop 0
	global_load_lds_dwordx4 v249, s[100:101]
	ds_read_b64_tr_b16 v[210:211], v240 offset:32768
	ds_read_b64_tr_b16 v[212:213], v240 offset:36864
	v_mfma_f32_16x16x32_bf16 v[118:121], v[178:181], v[174:177], v[118:121]
	v_add_f32_e32 v251, v103, v251
	v_add_f32_e32 v251, v104, v251
	s_waitcnt lgkmcnt(8)
	v_mfma_f32_16x16x32_bf16 v[122:125], v[182:185], v[158:161], v[122:125]
	v_add_f32_e32 v251, v105, v251
	ds_read_b64_tr_b16 v[214:215], v241 offset:32768
	ds_read_b64_tr_b16 v[216:217], v241 offset:36864
	v_mfma_f32_16x16x32_bf16 v[126:129], v[182:185], v[174:177], v[126:129]
	v_add_f32_e32 v251, v110, v251
	v_add_f32_e32 v251, v111, v251
	s_waitcnt lgkmcnt(7)
	v_mfma_f32_16x16x32_bf16 v[130:133], v[186:189], v[158:161], v[130:133]
	v_add_f32_e32 v251, v112, v251
	ds_read_b64_tr_b16 v[218:219], v242 offset:32768
	ds_read_b64_tr_b16 v[220:221], v242 offset:36864
	v_mfma_f32_16x16x32_bf16 v[134:137], v[186:189], v[174:177], v[134:137]
	v_add_f32_e32 v251, v113, v251
	v_cvt_pk_bf16_f32 v102, v102, v103
	s_waitcnt lgkmcnt(6)
; __device__ __forceinline__ void partialSM(f32x16& p0, f32x16& p1, float mC) {
;     ...
;   for (int r = 0; r < 16; ++r) p0[r] = __builtin_amdgcn_exp2f(p0[r]);
; }
; __device__ __forceinline__ void finishSM(f32x16& p0, f32x16& p1, float& l_reg, bf16x8& pa0, bf16x8& pa1, bf16x8& pa2, bf16x8& pa3) {
;   for (int r = 0; r < 16; ++r) p1[r] = __builtin_amdgcn_exp2f(p1[r]);
;   float ps = 0; for (int r = 0; r < 16; ++r) ps += p0[r]; for (int r = 0; r < 16; ++r) ps += p1[r];
;   { auto rr = __builtin_amdgcn_permlane32_swap(__float_as_uint(ps), __float_as_uint(ps), false, false);
;     ps = __uint_as_float(rr[0]) + __uint_as_float(rr[1]); }
;   l_reg += ps;
;     ...
;   PK4(p0, 0, pa0); PK4(p0, 8, pa1); PK4(p1, 0, pa2); PK4(p1, 8, pa3);
;     ...
; }
; __device__ __forceinline__ void qkt(f32x16& p0, f32x16& p1, const bf16* Ks, const bf16x8* qr, int r32, int hi, const f32x16& negm) {
; #pragma unroll
;   for (int d0 = 0; d0 < 8; ++d0) { int cb = (d0 * 16 + hi * 8) * 2;
;     bf16x8 b0 = *reinterpret_cast<const bf16x8*>((const char*)Ks + KSWZ(r32, cb));
;     bf16x8 b1 = *reinterpret_cast<const bf16x8*>((const char*)Ks + KSWZ(32 + r32, cb));
;     if (d0 == 0) { p0 = __builtin_amdgcn_mfma_f32_32x32x16_bf16(b0, qr[0], negm, 0, 0, 0); p1 = __builtin_amdgcn_mfma_f32_32x32x16_bf16(b1, qr[0], negm, 0, 0, 0); }
;     else { p0 = __builtin_amdgcn_mfma_f32_32x32x16_bf16(b0, qr[d0], p0, 0, 0, 0); p1 = __builtin_amdgcn_mfma_f32_32x32x16_bf16(b1, qr[d0], p1, 0, 0, 0); } }
; }
; __device__ __forceinline__ int v_st(int k, int c) { const int kk = (k & ~0xC) | ((k & 4) << 1) | ((k & 8) >> 1); return ((kk >> 3) * 4 + (c >> 5)) * 512 + ((kk & 7) * 32 + (c & 31)) * 2; }
; __device__ __forceinline__ int v_rd_base(int lane) { return ((lane & 3) << 3) | (((lane >> 2) & 3) << 6) | (((lane >> 4) & 1) << 5) | (((lane >> 5) & 1) << 8); }
; template <int OFF> __device__ __forceinline__ s16x4 tr_read(int vb) {
;   s16x4 r; asm volatile("ds_read_b64_tr_b16 %0, %1 offset:%2" : "=&v"(r) : "v"(vb), "i"(OFF) : "memory"); return r;
; }
; template <int D0> __device__ __forceinline__ void pv_one(f32x16& od, int vb, bf16x8 pa0, bf16x8 pa1, bf16x8 pa2, bf16x8 pa3) {
;   const s16x4 l0 = tr_read<v_rd_off(D0, 0, 0)>(vb), h0 = tr_read<v_rd_off(D0, 0, 1)>(vb), l1 = tr_read<v_rd_off(D0, 1, 0)>(vb), h1 = tr_read<v_rd_off(D0, 1, 1)>(vb);
	v_mfma_f32_16x16x32_bf16 v[138:141], v[190:193], v[158:161], v[138:141]
	v_cvt_pk_bf16_f32 v103, v104, v105
	ds_read_b64_tr_b16 v[222:223], v243 offset:32768
	ds_read_b64_tr_b16 v[224:225], v243 offset:36864
	v_mfma_f32_16x16x32_bf16 v[142:145], v[190:193], v[174:177], v[142:145]
	v_cvt_pk_bf16_f32 v104, v110, v111
	v_cvt_pk_bf16_f32 v105, v112, v113
	v_mfma_f32_16x16x32_bf16 v[18:21], v[202:205], v[82:85], v[18:21]
	v_exp_f32_e32 v114, v114
	v_mfma_f32_16x16x32_bf16 v[22:25], v[202:205], v[86:89], v[22:25]
	ds_read_b64_tr_b16 v[202:203], v244 offset:32768
	ds_read_b64_tr_b16 v[204:205], v244 offset:36864
	v_exp_f32_e32 v115, v115
	v_mfma_f32_16x16x32_bf16 v[26:29], v[206:209], v[82:85], v[26:29]
	v_exp_f32_e32 v116, v116
	v_mfma_f32_16x16x32_bf16 v[30:33], v[206:209], v[86:89], v[30:33]
	ds_read_b64_tr_b16 v[206:207], v245 offset:32768
	ds_read_b64_tr_b16 v[208:209], v245 offset:36864
	v_exp_f32_e32 v117, v117
	s_waitcnt lgkmcnt(10)
	v_mfma_f32_16x16x32_bf16 v[34:37], v[210:213], v[82:85], v[34:37]
	v_exp_f32_e32 v118, v118
	v_mfma_f32_16x16x32_bf16 v[38:41], v[210:213], v[86:89], v[38:41]
	ds_read_b64_tr_b16 v[210:211], v238 offset:40960
	ds_read_b64_tr_b16 v[212:213], v238 offset:45056
	v_exp_f32_e32 v119, v119
	s_waitcnt lgkmcnt(10)
	v_mfma_f32_16x16x32_bf16 v[42:45], v[214:217], v[82:85], v[42:45]
	v_exp_f32_e32 v120, v120
	v_mfma_f32_16x16x32_bf16 v[46:49], v[214:217], v[86:89], v[46:49]
	ds_read_b64_tr_b16 v[214:215], v239 offset:40960
	ds_read_b64_tr_b16 v[216:217], v239 offset:45056
	v_exp_f32_e32 v121, v121
	s_waitcnt lgkmcnt(10)
	v_mfma_f32_16x16x32_bf16 v[50:53], v[218:221], v[82:85], v[50:53]
	v_exp_f32_e32 v122, v122
	v_mfma_f32_16x16x32_bf16 v[54:57], v[218:221], v[86:89], v[54:57]
	ds_read_b64_tr_b16 v[218:219], v240 offset:40960
	ds_read_b64_tr_b16 v[220:221], v240 offset:45056
	v_exp_f32_e32 v123, v123
	s_waitcnt lgkmcnt(10)
	v_mfma_f32_16x16x32_bf16 v[58:61], v[222:225], v[82:85], v[58:61]
	v_exp_f32_e32 v124, v124
	v_mfma_f32_16x16x32_bf16 v[62:65], v[222:225], v[86:89], v[62:65]
	ds_read_b64_tr_b16 v[222:223], v241 offset:40960
	ds_read_b64_tr_b16 v[224:225], v241 offset:45056
	v_exp_f32_e32 v125, v125
	s_waitcnt lgkmcnt(10)
	v_mfma_f32_16x16x32_bf16 v[66:69], v[202:205], v[82:85], v[66:69]
	v_exp_f32_e32 v126, v126
	v_mfma_f32_16x16x32_bf16 v[70:73], v[202:205], v[86:89], v[70:73]
	ds_read_b64_tr_b16 v[202:203], v242 offset:40960
	ds_read_b64_tr_b16 v[204:205], v242 offset:45056
	v_exp_f32_e32 v127, v127
	s_waitcnt lgkmcnt(10)
	v_mfma_f32_16x16x32_bf16 v[74:77], v[206:209], v[82:85], v[74:77]
	v_exp_f32_e32 v128, v128
	v_mfma_f32_16x16x32_bf16 v[78:81], v[206:209], v[86:89], v[78:81]
	ds_read_b64_tr_b16 v[206:207], v243 offset:40960
	ds_read_b64_tr_b16 v[208:209], v243 offset:45056
	v_exp_f32_e32 v129, v129
	s_waitcnt lgkmcnt(10)
	v_mfma_f32_16x16x32_bf16 v[18:21], v[210:213], v[98:101], v[18:21]
	v_exp_f32_e32 v130, v130
	v_mfma_f32_16x16x32_bf16 v[22:25], v[210:213], v[102:105], v[22:25]
	ds_read_b64_tr_b16 v[210:211], v244 offset:40960
	ds_read_b64_tr_b16 v[212:213], v244 offset:45056
	v_exp_f32_e32 v131, v131
	s_waitcnt lgkmcnt(10)
	v_mfma_f32_16x16x32_bf16 v[26:29], v[214:217], v[98:101], v[26:29]
	v_exp_f32_e32 v132, v132
	v_mfma_f32_16x16x32_bf16 v[30:33], v[214:217], v[102:105], v[30:33]
	ds_read_b64_tr_b16 v[214:215], v245 offset:40960
	ds_read_b64_tr_b16 v[216:217], v245 offset:45056
	v_exp_f32_e32 v133, v133
	s_waitcnt lgkmcnt(10)
	v_mfma_f32_16x16x32_bf16 v[34:37], v[218:221], v[98:101], v[34:37]
	v_exp_f32_e32 v134, v134
	v_mfma_f32_16x16x32_bf16 v[38:41], v[218:221], v[102:105], v[38:41]
	v_exp_f32_e32 v135, v135
	s_waitcnt lgkmcnt(8)
	v_mfma_f32_16x16x32_bf16 v[42:45], v[222:225], v[98:101], v[42:45]
	v_exp_f32_e32 v136, v136
	v_mfma_f32_16x16x32_bf16 v[46:49], v[222:225], v[102:105], v[46:49]
	v_exp_f32_e32 v137, v137
	s_waitcnt lgkmcnt(6)
	v_mfma_f32_16x16x32_bf16 v[50:53], v[202:205], v[98:101], v[50:53]
	v_exp_f32_e32 v138, v138
	ds_read_b128 v[178:181], v234 offset:0
	v_mfma_f32_16x16x32_bf16 v[54:57], v[202:205], v[102:105], v[54:57]
	v_exp_f32_e32 v139, v139
	s_waitcnt lgkmcnt(5)
	v_mfma_f32_16x16x32_bf16 v[58:61], v[206:209], v[98:101], v[58:61]
	v_exp_f32_e32 v140, v140
	ds_read_b128 v[182:185], v234 offset:4096
	v_mfma_f32_16x16x32_bf16 v[62:65], v[206:209], v[102:105], v[62:65]
	v_exp_f32_e32 v141, v141
	s_waitcnt lgkmcnt(4)
	v_mfma_f32_16x16x32_bf16 v[66:69], v[210:213], v[98:101], v[66:69]
	v_exp_f32_e32 v142, v142
	ds_read_b128 v[186:189], v234 offset:8192
	v_mfma_f32_16x16x32_bf16 v[70:73], v[210:213], v[102:105], v[70:73]
	v_exp_f32_e32 v143, v143
	s_waitcnt lgkmcnt(3)
	v_mfma_f32_16x16x32_bf16 v[74:77], v[214:217], v[98:101], v[74:77]
	v_exp_f32_e32 v144, v144
	ds_read_b128 v[190:193], v234 offset:12288
	v_mfma_f32_16x16x32_bf16 v[78:81], v[214:217], v[102:105], v[78:81]
	v_exp_f32_e32 v145, v145
	s_waitcnt vmcnt(4)
	s_barrier
; #define SBAR() __builtin_amdgcn_sched_barrier(0)
; #define SLOAD(i, k0) do { sr_[i].vs0 = St::ld8(&Vh[(long)((k0) + sr) * LDK + sc]); sr_[i].vs1 = St::ld8(&Vh[(long)((k0) + 32 + sr) * LDK + sc]); \
;     sr_[i].ks0 = St::ld8(&Kh[(long)((k0) + sr) * LDK + sc]); sr_[i].ks1 = St::ld8(&Kh[(long)((k0) + 32 + sr) * LDK + sc]); } while (0)
; #define SWAIT() do { if constexpr (SDEPTH == 2) asm volatile("s_waitcnt vmcnt(4)" ::: "memory"); else asm volatile("s_waitcnt vmcnt(0)" ::: "memory"); } while (0)
; __device__ __forceinline__ void finishSM(f32x16& p0, f32x16& p1, float& l_reg, bf16x8& pa0, bf16x8& pa1, bf16x8& pa2, bf16x8& pa3) {
;   for (int r = 0; r < 16; ++r) p1[r] = __builtin_amdgcn_exp2f(p1[r]);
;   float ps = 0; for (int r = 0; r < 16; ++r) ps += p0[r]; for (int r = 0; r < 16; ++r) ps += p1[r];
;   { auto rr = __builtin_amdgcn_permlane32_swap(__float_as_uint(ps), __float_as_uint(ps), false, false);
;     ps = __uint_as_float(rr[0]) + __uint_as_float(rr[1]); }
;   l_reg += ps;
;     ...
;   PK4(p0, 0, pa0); PK4(p0, 8, pa1); PK4(p1, 0, pa2); PK4(p1, 8, pa3);
;     ...
; }
; __device__ __forceinline__ void qkt(f32x16& p0, f32x16& p1, const bf16* Ks, const bf16x8* qr, int r32, int hi, const f32x16& negm) {
; #pragma unroll
;   for (int d0 = 0; d0 < 8; ++d0) { int cb = (d0 * 16 + hi * 8) * 2;
;     bf16x8 b0 = *reinterpret_cast<const bf16x8*>((const char*)Ks + KSWZ(r32, cb));
;     bf16x8 b1 = *reinterpret_cast<const bf16x8*>((const char*)Ks + KSWZ(32 + r32, cb));
;     if (d0 == 0) { p0 = __builtin_amdgcn_mfma_f32_32x32x16_bf16(b0, qr[0], negm, 0, 0, 0); p1 = __builtin_amdgcn_mfma_f32_32x32x16_bf16(b1, qr[0], negm, 0, 0, 0); }
;     else { p0 = __builtin_amdgcn_mfma_f32_32x32x16_bf16(b0, qr[d0], p0, 0, 0, 0); p1 = __builtin_amdgcn_mfma_f32_32x32x16_bf16(b1, qr[d0], p1, 0, 0, 0); } }
; }
; template <typename TQ> ...
;     ...
;   for (int j = 1; j + 1 < NT; j += 2) {
;     SBAR(); SLOAD(SO, (j + SDEPTH) * KVBLK); SBAR();
;     qkt(pB0, pB1, (bf16*)((char*)K_lds + SHM_K), qr, r32, hi, negm);
;     finishSM(pA0, pA1, l_reg, pa0, pa1, pa2, pa3); SBAR();
;     pv_d0(o, vb0, pa0, pa1, pa2, pa3); partialSM(pB0, pB1, mC);
;     __syncthreads(); SWAIT(); SWRITE(0, SE);
;     __syncthreads();
;     SBAR(); if (SDEPTH == 1 || j + 3 < NT) SLOAD(SE, (j + 1 + SDEPTH) * KVBLK); SBAR();
	s_waitcnt lgkmcnt(3)
	v_mfma_f32_16x16x32_bf16 v[82:85], v[178:181], v[146:149], v[2:5]
	v_add_f32_e32 v250, v114, v250
	s_add_u32 s98, s98, 0x8000
	s_addc_u32 s99, s99, 0
	s_add_u32 s100, s100, 0x8000
	s_addc_u32 s101, s101, 0
	s_add_u32 m0, s79, 49152
	s_nop 0
	global_load_lds_dwordx4 v246, s[98:99]
	v_mfma_f32_16x16x32_bf16 v[86:89], v[178:181], v[162:165], v[2:5]
	ds_read_b128 v[178:181], v235 offset:0
	v_add_f32_e32 v250, v115, v250
	v_add_f32_e32 v250, v116, v250
	s_waitcnt lgkmcnt(3)
	v_mfma_f32_16x16x32_bf16 v[90:93], v[182:185], v[146:149], v[2:5]
	v_add_f32_e32 v250, v117, v250
	v_mfma_f32_16x16x32_bf16 v[94:97], v[182:185], v[162:165], v[2:5]
	ds_read_b128 v[182:185], v235 offset:4096
	v_add_f32_e32 v250, v122, v250
	v_add_f32_e32 v250, v123, v250
	s_waitcnt lgkmcnt(3)
	v_mfma_f32_16x16x32_bf16 v[98:101], v[186:189], v[146:149], v[2:5]
	v_add_f32_e32 v250, v124, v250
	v_mfma_f32_16x16x32_bf16 v[102:105], v[186:189], v[162:165], v[2:5]
	ds_read_b128 v[186:189], v235 offset:8192
	v_add_f32_e32 v250, v125, v250
	v_cvt_pk_bf16_f32 v114, v114, v115
	s_waitcnt lgkmcnt(3)
	v_mfma_f32_16x16x32_bf16 v[106:109], v[190:193], v[146:149], v[2:5]
	v_cvt_pk_bf16_f32 v115, v116, v117
	v_mfma_f32_16x16x32_bf16 v[110:113], v[190:193], v[162:165], v[2:5]
	ds_read_b128 v[190:193], v235 offset:12288
	v_cvt_pk_bf16_f32 v116, v122, v123
	v_cvt_pk_bf16_f32 v117, v124, v125
	s_waitcnt lgkmcnt(3)
	v_mfma_f32_16x16x32_bf16 v[82:85], v[178:181], v[150:153], v[82:85]
	v_add_f32_e32 v251, v118, v251
	s_add_u32 m0, s79, 50176
	s_nop 0
	global_load_lds_dwordx4 v247, s[98:99]
	v_mfma_f32_16x16x32_bf16 v[86:89], v[178:181], v[166:169], v[86:89]
	ds_read_b128 v[178:181], v236 offset:0
	v_add_f32_e32 v251, v119, v251
	v_add_f32_e32 v251, v120, v251
	s_waitcnt lgkmcnt(3)
	v_mfma_f32_16x16x32_bf16 v[90:93], v[182:185], v[150:153], v[90:93]
	v_add_f32_e32 v251, v121, v251
	v_mfma_f32_16x16x32_bf16 v[94:97], v[182:185], v[166:169], v[94:97]
	ds_read_b128 v[182:185], v236 offset:4096
	v_add_f32_e32 v251, v126, v251
	v_add_f32_e32 v251, v127, v251
	s_waitcnt lgkmcnt(3)
	v_mfma_f32_16x16x32_bf16 v[98:101], v[186:189], v[150:153], v[98:101]
	v_add_f32_e32 v251, v128, v251
	v_mfma_f32_16x16x32_bf16 v[102:105], v[186:189], v[166:169], v[102:105]
	ds_read_b128 v[186:189], v236 offset:8192
	v_add_f32_e32 v251, v129, v251
	v_cvt_pk_bf16_f32 v118, v118, v119
	s_waitcnt lgkmcnt(3)
	v_mfma_f32_16x16x32_bf16 v[106:109], v[190:193], v[150:153], v[106:109]
	v_cvt_pk_bf16_f32 v119, v120, v121
	v_mfma_f32_16x16x32_bf16 v[110:113], v[190:193], v[166:169], v[110:113]
	ds_read_b128 v[190:193], v236 offset:12288
	v_cvt_pk_bf16_f32 v120, v126, v127
	v_cvt_pk_bf16_f32 v121, v128, v129
	s_waitcnt lgkmcnt(3)
	v_mfma_f32_16x16x32_bf16 v[82:85], v[178:181], v[154:157], v[82:85]
	v_add_f32_e32 v250, v130, v250
	s_add_u32 m0, s80, 32768
	s_nop 0
	global_load_lds_dwordx4 v248, s[100:101]
	v_mfma_f32_16x16x32_bf16 v[86:89], v[178:181], v[170:173], v[86:89]
	ds_read_b128 v[178:181], v237 offset:0
	v_add_f32_e32 v250, v131, v250
	v_add_f32_e32 v250, v132, v250
	s_waitcnt lgkmcnt(3)
	v_mfma_f32_16x16x32_bf16 v[90:93], v[182:185], v[154:157], v[90:93]
	v_add_f32_e32 v250, v133, v250
	v_mfma_f32_16x16x32_bf16 v[94:97], v[182:185], v[170:173], v[94:97]
	ds_read_b128 v[182:185], v237 offset:4096
	v_add_f32_e32 v250, v138, v250
	v_add_f32_e32 v250, v139, v250
	s_waitcnt lgkmcnt(3)
	v_mfma_f32_16x16x32_bf16 v[98:101], v[186:189], v[154:157], v[98:101]
	v_add_f32_e32 v250, v140, v250
	ds_read_b64_tr_b16 v[202:203], v238 offset:49152
	ds_read_b64_tr_b16 v[204:205], v238 offset:53248
	v_mfma_f32_16x16x32_bf16 v[102:105], v[186:189], v[170:173], v[102:105]
	ds_read_b128 v[186:189], v237 offset:8192
	v_add_f32_e32 v250, v141, v250
	v_cvt_pk_bf16_f32 v130, v130, v131
	s_waitcnt lgkmcnt(5)
	v_mfma_f32_16x16x32_bf16 v[106:109], v[190:193], v[154:157], v[106:109]
	v_cvt_pk_bf16_f32 v131, v132, v133
	ds_read_b64_tr_b16 v[206:207], v239 offset:49152
	ds_read_b64_tr_b16 v[208:209], v239 offset:53248
	v_mfma_f32_16x16x32_bf16 v[110:113], v[190:193], v[170:173], v[110:113]
	ds_read_b128 v[190:193], v237 offset:12288
	v_cvt_pk_bf16_f32 v132, v138, v139
	v_cvt_pk_bf16_f32 v133, v140, v141
	s_waitcnt lgkmcnt(7)
	v_mfma_f32_16x16x32_bf16 v[82:85], v[178:181], v[158:161], v[82:85]
	v_add_f32_e32 v251, v134, v251
	s_add_u32 m0, s80, 33792
	s_nop 0
	global_load_lds_dwordx4 v249, s[100:101]
	ds_read_b64_tr_b16 v[210:211], v240 offset:49152
	ds_read_b64_tr_b16 v[212:213], v240 offset:53248
	v_mfma_f32_16x16x32_bf16 v[86:89], v[178:181], v[174:177], v[86:89]
	v_add_f32_e32 v251, v135, v251
	v_add_f32_e32 v251, v136, v251
	s_waitcnt lgkmcnt(8)
	v_mfma_f32_16x16x32_bf16 v[90:93], v[182:185], v[158:161], v[90:93]
	v_add_f32_e32 v251, v137, v251
	ds_read_b64_tr_b16 v[214:215], v241 offset:49152
	ds_read_b64_tr_b16 v[216:217], v241 offset:53248
	v_mfma_f32_16x16x32_bf16 v[94:97], v[182:185], v[174:177], v[94:97]
	v_add_f32_e32 v251, v142, v251
	v_add_f32_e32 v251, v143, v251
	s_waitcnt lgkmcnt(7)
	v_mfma_f32_16x16x32_bf16 v[98:101], v[186:189], v[158:161], v[98:101]
	v_add_f32_e32 v251, v144, v251
	ds_read_b64_tr_b16 v[218:219], v242 offset:49152
	ds_read_b64_tr_b16 v[220:221], v242 offset:53248
	v_mfma_f32_16x16x32_bf16 v[102:105], v[186:189], v[174:177], v[102:105]
	v_add_f32_e32 v251, v145, v251
	v_cvt_pk_bf16_f32 v134, v134, v135
	s_waitcnt lgkmcnt(6)
; #define SBAR() __builtin_amdgcn_sched_barrier(0)
; #define SLOAD(i, k0) do { sr_[i].vs0 = St::ld8(&Vh[(long)((k0) + sr) * LDK + sc]); sr_[i].vs1 = St::ld8(&Vh[(long)((k0) + 32 + sr) * LDK + sc]); \
;     sr_[i].ks0 = St::ld8(&Kh[(long)((k0) + sr) * LDK + sc]); sr_[i].ks1 = St::ld8(&Kh[(long)((k0) + 32 + sr) * LDK + sc]); } while (0)
; #define SWAIT() do { if constexpr (SDEPTH == 2) asm volatile("s_waitcnt vmcnt(4)" ::: "memory"); else asm volatile("s_waitcnt vmcnt(0)" ::: "memory"); } while (0)
; template <int D0> __device__ __forceinline__ void pv_one(f32x16& od, int vb, bf16x8 pa0, bf16x8 pa1, bf16x8 pa2, bf16x8 pa3) {
;   const s16x4 l0 = tr_read<v_rd_off(D0, 0, 0)>(vb), h0 = tr_read<v_rd_off(D0, 0, 1)>(vb), l1 = tr_read<v_rd_off(D0, 1, 0)>(vb), h1 = tr_read<v_rd_off(D0, 1, 1)>(vb);
;   const s16x4 l2 = tr_read<v_rd_off(D0, 2, 0)>(vb), h2 = tr_read<v_rd_off(D0, 2, 1)>(vb), l3 = tr_read<v_rd_off(D0, 3, 0)>(vb), h3 = tr_read<v_rd_off(D0, 3, 1)>(vb);
;   asm volatile("s_waitcnt lgkmcnt(0)" ::: "memory"); SBAR();
;     ...
;   od = __builtin_amdgcn_mfma_f32_32x32x16_bf16(pa0, PK(l0, h0), od, 0, 0, 0);
;   od = __builtin_amdgcn_mfma_f32_32x32x16_bf16(pa1, PK(l1, h1), od, 0, 0, 0);
;   od = __builtin_amdgcn_mfma_f32_32x32x16_bf16(pa2, PK(l2, h2), od, 0, 0, 0);
;   od = __builtin_amdgcn_mfma_f32_32x32x16_bf16(pa3, PK(l3, h3), od, 0, 0, 0);
;     ...
; }
; __device__ __forceinline__ void pv_d0(f32x16* o, int vb, bf16x8 pa0, bf16x8 pa1, bf16x8 pa2, bf16x8 pa3) {
;   pv_one<0>(o[0], vb, pa0, pa1, pa2, pa3); pv_one<1>(o[1], vb, pa0, pa1, pa2, pa3); pv_one<2>(o[2], vb, pa0, pa1, pa2, pa3); pv_one<3>(o[3], vb, pa0, pa1, pa2, pa3);
; template <typename TQ> ...
;     ...
;   for (int j = 1; j + 1 < NT; j += 2) {
;     SBAR(); SLOAD(SO, (j + SDEPTH) * KVBLK); SBAR();
;     qkt(pB0, pB1, (bf16*)((char*)K_lds + SHM_K), qr, r32, hi, negm);
;     finishSM(pA0, pA1, l_reg, pa0, pa1, pa2, pa3); SBAR();
;     pv_d0(o, vb0, pa0, pa1, pa2, pa3); partialSM(pB0, pB1, mC);
;     __syncthreads(); SWAIT(); SWRITE(0, SE);
;     __syncthreads();
;     SBAR(); if (SDEPTH == 1 || j + 3 < NT) SLOAD(SE, (j + 1 + SDEPTH) * KVBLK); SBAR();
;     qkt(pA0, pA1, K_lds, qr, r32, hi, negm);
;     finishSM(pB0, pB1, l_reg, pa0, pa1, pa2, pa3); SBAR();
;     pv_d0(o, vb0 + (int)SHM_V, pa0, pa1, pa2, pa3); partialSM(pA0, pA1, mC);
;     __syncthreads(); SWAIT(); SWRITE(1, SO);
;     __syncthreads();
;   }
	v_mfma_f32_16x16x32_bf16 v[106:109], v[190:193], v[158:161], v[106:109]
	v_cvt_pk_bf16_f32 v135, v136, v137
	ds_read_b64_tr_b16 v[222:223], v243 offset:49152
	ds_read_b64_tr_b16 v[224:225], v243 offset:53248
	v_mfma_f32_16x16x32_bf16 v[110:113], v[190:193], v[174:177], v[110:113]
	v_cvt_pk_bf16_f32 v136, v142, v143
	v_cvt_pk_bf16_f32 v137, v144, v145
	v_mfma_f32_16x16x32_bf16 v[18:21], v[202:205], v[114:117], v[18:21]
	v_exp_f32_e32 v82, v82
	v_mfma_f32_16x16x32_bf16 v[22:25], v[202:205], v[118:121], v[22:25]
	ds_read_b64_tr_b16 v[202:203], v244 offset:49152
	ds_read_b64_tr_b16 v[204:205], v244 offset:53248
	v_exp_f32_e32 v83, v83
	v_mfma_f32_16x16x32_bf16 v[26:29], v[206:209], v[114:117], v[26:29]
	v_exp_f32_e32 v84, v84
	v_mfma_f32_16x16x32_bf16 v[30:33], v[206:209], v[118:121], v[30:33]
	ds_read_b64_tr_b16 v[206:207], v245 offset:49152
	ds_read_b64_tr_b16 v[208:209], v245 offset:53248
	v_exp_f32_e32 v85, v85
	s_waitcnt lgkmcnt(10)
	v_mfma_f32_16x16x32_bf16 v[34:37], v[210:213], v[114:117], v[34:37]
	v_exp_f32_e32 v86, v86
	v_mfma_f32_16x16x32_bf16 v[38:41], v[210:213], v[118:121], v[38:41]
	ds_read_b64_tr_b16 v[210:211], v238 offset:57344
	ds_read_b64_tr_b16 v[212:213], v238 offset:61440
	v_exp_f32_e32 v87, v87
	s_waitcnt lgkmcnt(10)
	v_mfma_f32_16x16x32_bf16 v[42:45], v[214:217], v[114:117], v[42:45]
	v_exp_f32_e32 v88, v88
	v_mfma_f32_16x16x32_bf16 v[46:49], v[214:217], v[118:121], v[46:49]
	ds_read_b64_tr_b16 v[214:215], v239 offset:57344
	ds_read_b64_tr_b16 v[216:217], v239 offset:61440
	v_exp_f32_e32 v89, v89
	s_waitcnt lgkmcnt(10)
	v_mfma_f32_16x16x32_bf16 v[50:53], v[218:221], v[114:117], v[50:53]
	v_exp_f32_e32 v90, v90
	v_mfma_f32_16x16x32_bf16 v[54:57], v[218:221], v[118:121], v[54:57]
	ds_read_b64_tr_b16 v[218:219], v240 offset:57344
	ds_read_b64_tr_b16 v[220:221], v240 offset:61440
	v_exp_f32_e32 v91, v91
	s_waitcnt lgkmcnt(10)
	v_mfma_f32_16x16x32_bf16 v[58:61], v[222:225], v[114:117], v[58:61]
	v_exp_f32_e32 v92, v92
	v_mfma_f32_16x16x32_bf16 v[62:65], v[222:225], v[118:121], v[62:65]
	ds_read_b64_tr_b16 v[222:223], v241 offset:57344
	ds_read_b64_tr_b16 v[224:225], v241 offset:61440
	v_exp_f32_e32 v93, v93
	s_waitcnt lgkmcnt(10)
	v_mfma_f32_16x16x32_bf16 v[66:69], v[202:205], v[114:117], v[66:69]
	v_exp_f32_e32 v94, v94
	v_mfma_f32_16x16x32_bf16 v[70:73], v[202:205], v[118:121], v[70:73]
	ds_read_b64_tr_b16 v[202:203], v242 offset:57344
	ds_read_b64_tr_b16 v[204:205], v242 offset:61440
	v_exp_f32_e32 v95, v95
	s_waitcnt lgkmcnt(10)
	v_mfma_f32_16x16x32_bf16 v[74:77], v[206:209], v[114:117], v[74:77]
	v_exp_f32_e32 v96, v96
	v_mfma_f32_16x16x32_bf16 v[78:81], v[206:209], v[118:121], v[78:81]
	ds_read_b64_tr_b16 v[206:207], v243 offset:57344
	ds_read_b64_tr_b16 v[208:209], v243 offset:61440
	v_exp_f32_e32 v97, v97
	s_waitcnt lgkmcnt(10)
	v_mfma_f32_16x16x32_bf16 v[18:21], v[210:213], v[130:133], v[18:21]
	v_exp_f32_e32 v98, v98
	v_mfma_f32_16x16x32_bf16 v[22:25], v[210:213], v[134:137], v[22:25]
	ds_read_b64_tr_b16 v[210:211], v244 offset:57344
	ds_read_b64_tr_b16 v[212:213], v244 offset:61440
	v_exp_f32_e32 v99, v99
	s_waitcnt lgkmcnt(10)
	v_mfma_f32_16x16x32_bf16 v[26:29], v[214:217], v[130:133], v[26:29]
	v_exp_f32_e32 v100, v100
	v_mfma_f32_16x16x32_bf16 v[30:33], v[214:217], v[134:137], v[30:33]
	ds_read_b64_tr_b16 v[214:215], v245 offset:57344
	ds_read_b64_tr_b16 v[216:217], v245 offset:61440
	v_exp_f32_e32 v101, v101
	s_waitcnt lgkmcnt(10)
	v_mfma_f32_16x16x32_bf16 v[34:37], v[218:221], v[130:133], v[34:37]
	v_exp_f32_e32 v102, v102
	v_mfma_f32_16x16x32_bf16 v[38:41], v[218:221], v[134:137], v[38:41]
	v_exp_f32_e32 v103, v103
	s_waitcnt lgkmcnt(8)
	v_mfma_f32_16x16x32_bf16 v[42:45], v[222:225], v[130:133], v[42:45]
	v_exp_f32_e32 v104, v104
	v_mfma_f32_16x16x32_bf16 v[46:49], v[222:225], v[134:137], v[46:49]
	v_exp_f32_e32 v105, v105
	s_waitcnt lgkmcnt(6)
	v_mfma_f32_16x16x32_bf16 v[50:53], v[202:205], v[130:133], v[50:53]
	v_exp_f32_e32 v106, v106
	ds_read_b128 v[178:181], v234 offset:16384
	v_mfma_f32_16x16x32_bf16 v[54:57], v[202:205], v[134:137], v[54:57]
	v_exp_f32_e32 v107, v107
	s_waitcnt lgkmcnt(5)
	v_mfma_f32_16x16x32_bf16 v[58:61], v[206:209], v[130:133], v[58:61]
	v_exp_f32_e32 v108, v108
	ds_read_b128 v[182:185], v234 offset:20480
	v_mfma_f32_16x16x32_bf16 v[62:65], v[206:209], v[134:137], v[62:65]
	v_exp_f32_e32 v109, v109
	s_waitcnt lgkmcnt(4)
	v_mfma_f32_16x16x32_bf16 v[66:69], v[210:213], v[130:133], v[66:69]
	v_exp_f32_e32 v110, v110
	ds_read_b128 v[186:189], v234 offset:24576
	v_mfma_f32_16x16x32_bf16 v[70:73], v[210:213], v[134:137], v[70:73]
	v_exp_f32_e32 v111, v111
	s_waitcnt lgkmcnt(3)
	v_mfma_f32_16x16x32_bf16 v[74:77], v[214:217], v[130:133], v[74:77]
	v_exp_f32_e32 v112, v112
	ds_read_b128 v[190:193], v234 offset:28672
	v_mfma_f32_16x16x32_bf16 v[78:81], v[214:217], v[134:137], v[78:81]
	v_exp_f32_e32 v113, v113
	s_waitcnt vmcnt(4)
	s_add_i32 s15, s15, 1
	s_cmp_lt_u32 s15, 32
	s_cbranch_scc1 .Lattn_loop
	s_barrier
; #define SBAR() __builtin_amdgcn_sched_barrier(0)
; __device__ __forceinline__ void finishSM(f32x16& p0, f32x16& p1, float& l_reg, bf16x8& pa0, bf16x8& pa1, bf16x8& pa2, bf16x8& pa3) {
;   for (int r = 0; r < 16; ++r) p1[r] = __builtin_amdgcn_exp2f(p1[r]);
;   float ps = 0; for (int r = 0; r < 16; ++r) ps += p0[r]; for (int r = 0; r < 16; ++r) ps += p1[r];
;   { auto rr = __builtin_amdgcn_permlane32_swap(__float_as_uint(ps), __float_as_uint(ps), false, false);
;     ps = __uint_as_float(rr[0]) + __uint_as_float(rr[1]); }
;   l_reg += ps;
;     ...
;   PK4(p0, 0, pa0); PK4(p0, 8, pa1); PK4(p1, 0, pa2); PK4(p1, 8, pa3);
;     ...
; }
; __device__ __forceinline__ void qkt(f32x16& p0, f32x16& p1, const bf16* Ks, const bf16x8* qr, int r32, int hi, const f32x16& negm) {
; #pragma unroll
;   for (int d0 = 0; d0 < 8; ++d0) { int cb = (d0 * 16 + hi * 8) * 2;
;     bf16x8 b0 = *reinterpret_cast<const bf16x8*>((const char*)Ks + KSWZ(r32, cb));
;     bf16x8 b1 = *reinterpret_cast<const bf16x8*>((const char*)Ks + KSWZ(32 + r32, cb));
;     if (d0 == 0) { p0 = __builtin_amdgcn_mfma_f32_32x32x16_bf16(b0, qr[0], negm, 0, 0, 0); p1 = __builtin_amdgcn_mfma_f32_32x32x16_bf16(b1, qr[0], negm, 0, 0, 0); }
;     else { p0 = __builtin_amdgcn_mfma_f32_32x32x16_bf16(b0, qr[d0], p0, 0, 0, 0); p1 = __builtin_amdgcn_mfma_f32_32x32x16_bf16(b1, qr[d0], p1, 0, 0, 0); } }
; }
; template <typename TQ> ...
;     ...
;   SBAR(); qkt(pB0, pB1, (bf16*)((char*)K_lds + SHM_K), qr, r32, hi, negm);
;   finishSM(pA0, pA1, l_reg, pa0, pa1, pa2, pa3); SBAR();
;   pv_d0(o, vb0, pa0, pa1, pa2, pa3); partialSM(pB0, pB1, mC);
	s_waitcnt lgkmcnt(3)
	v_mfma_f32_16x16x32_bf16 v[114:117], v[178:181], v[146:149], v[2:5]
	v_add_f32_e32 v250, v82, v250
	s_add_u32 s98, s98, 0x8000
	s_addc_u32 s99, s99, 0
	s_add_u32 s100, s100, 0x8000
	s_addc_u32 s101, s101, 0
	s_add_u32 m0, s80, 49152
	s_nop 0
	global_load_lds_dwordx4 v248, s[100:101]
	v_mfma_f32_16x16x32_bf16 v[118:121], v[178:181], v[162:165], v[2:5]
	ds_read_b128 v[178:181], v235 offset:16384
	v_add_f32_e32 v250, v83, v250
	v_add_f32_e32 v250, v84, v250
	s_waitcnt lgkmcnt(3)
	v_mfma_f32_16x16x32_bf16 v[122:125], v[182:185], v[146:149], v[2:5]
	v_add_f32_e32 v250, v85, v250
	v_mfma_f32_16x16x32_bf16 v[126:129], v[182:185], v[162:165], v[2:5]
	ds_read_b128 v[182:185], v235 offset:20480
	v_add_f32_e32 v250, v90, v250
	v_add_f32_e32 v250, v91, v250
	s_waitcnt lgkmcnt(3)
	v_mfma_f32_16x16x32_bf16 v[130:133], v[186:189], v[146:149], v[2:5]
	v_add_f32_e32 v250, v92, v250
	v_mfma_f32_16x16x32_bf16 v[134:137], v[186:189], v[162:165], v[2:5]
	ds_read_b128 v[186:189], v235 offset:24576
	v_add_f32_e32 v250, v93, v250
	v_cvt_pk_bf16_f32 v82, v82, v83
	s_waitcnt lgkmcnt(3)
	v_mfma_f32_16x16x32_bf16 v[138:141], v[190:193], v[146:149], v[2:5]
	v_cvt_pk_bf16_f32 v83, v84, v85
	v_mfma_f32_16x16x32_bf16 v[142:145], v[190:193], v[162:165], v[2:5]
	ds_read_b128 v[190:193], v235 offset:28672
	v_cvt_pk_bf16_f32 v84, v90, v91
	v_cvt_pk_bf16_f32 v85, v92, v93
	s_waitcnt lgkmcnt(3)
	v_mfma_f32_16x16x32_bf16 v[114:117], v[178:181], v[150:153], v[114:117]
	v_add_f32_e32 v251, v86, v251
	s_add_u32 m0, s80, 50176
	s_nop 0
	global_load_lds_dwordx4 v249, s[100:101]
	v_mfma_f32_16x16x32_bf16 v[118:121], v[178:181], v[166:169], v[118:121]
	ds_read_b128 v[178:181], v236 offset:16384
	v_add_f32_e32 v251, v87, v251
	v_add_f32_e32 v251, v88, v251
	s_waitcnt lgkmcnt(3)
	v_mfma_f32_16x16x32_bf16 v[122:125], v[182:185], v[150:153], v[122:125]
	v_add_f32_e32 v251, v89, v251
	v_mfma_f32_16x16x32_bf16 v[126:129], v[182:185], v[166:169], v[126:129]
	ds_read_b128 v[182:185], v236 offset:20480
	v_add_f32_e32 v251, v94, v251
	v_add_f32_e32 v251, v95, v251
	s_waitcnt lgkmcnt(3)
	v_mfma_f32_16x16x32_bf16 v[130:133], v[186:189], v[150:153], v[130:133]
	v_add_f32_e32 v251, v96, v251
	v_mfma_f32_16x16x32_bf16 v[134:137], v[186:189], v[166:169], v[134:137]
	ds_read_b128 v[186:189], v236 offset:24576
	v_add_f32_e32 v251, v97, v251
	v_cvt_pk_bf16_f32 v86, v86, v87
	s_waitcnt lgkmcnt(3)
	v_mfma_f32_16x16x32_bf16 v[138:141], v[190:193], v[150:153], v[138:141]
	v_cvt_pk_bf16_f32 v87, v88, v89
	v_mfma_f32_16x16x32_bf16 v[142:145], v[190:193], v[166:169], v[142:145]
	ds_read_b128 v[190:193], v236 offset:28672
	v_cvt_pk_bf16_f32 v88, v94, v95
	v_cvt_pk_bf16_f32 v89, v96, v97
	s_waitcnt lgkmcnt(3)
	v_mfma_f32_16x16x32_bf16 v[114:117], v[178:181], v[154:157], v[114:117]
	v_add_f32_e32 v250, v98, v250
	v_mfma_f32_16x16x32_bf16 v[118:121], v[178:181], v[170:173], v[118:121]
	ds_read_b128 v[178:181], v237 offset:16384
	v_add_f32_e32 v250, v99, v250
	v_add_f32_e32 v250, v100, v250
	s_waitcnt lgkmcnt(3)
	v_mfma_f32_16x16x32_bf16 v[122:125], v[182:185], v[154:157], v[122:125]
	v_add_f32_e32 v250, v101, v250
	v_mfma_f32_16x16x32_bf16 v[126:129], v[182:185], v[170:173], v[126:129]
	ds_read_b128 v[182:185], v237 offset:20480
	v_add_f32_e32 v250, v106, v250
	v_add_f32_e32 v250, v107, v250
	s_waitcnt lgkmcnt(3)
	v_mfma_f32_16x16x32_bf16 v[130:133], v[186:189], v[154:157], v[130:133]
	v_add_f32_e32 v250, v108, v250
	ds_read_b64_tr_b16 v[202:203], v238 offset:0
	ds_read_b64_tr_b16 v[204:205], v238 offset:4096
	v_mfma_f32_16x16x32_bf16 v[134:137], v[186:189], v[170:173], v[134:137]
	ds_read_b128 v[186:189], v237 offset:24576
	v_add_f32_e32 v250, v109, v250
	v_cvt_pk_bf16_f32 v98, v98, v99
	s_waitcnt lgkmcnt(5)
	v_mfma_f32_16x16x32_bf16 v[138:141], v[190:193], v[154:157], v[138:141]
	v_cvt_pk_bf16_f32 v99, v100, v101
	ds_read_b64_tr_b16 v[206:207], v239 offset:0
	ds_read_b64_tr_b16 v[208:209], v239 offset:4096
	v_mfma_f32_16x16x32_bf16 v[142:145], v[190:193], v[170:173], v[142:145]
	ds_read_b128 v[190:193], v237 offset:28672
	v_cvt_pk_bf16_f32 v100, v106, v107
	v_cvt_pk_bf16_f32 v101, v108, v109
	s_waitcnt lgkmcnt(7)
	v_mfma_f32_16x16x32_bf16 v[114:117], v[178:181], v[158:161], v[114:117]
	v_add_f32_e32 v251, v102, v251
	ds_read_b64_tr_b16 v[210:211], v240 offset:0
	ds_read_b64_tr_b16 v[212:213], v240 offset:4096
	v_mfma_f32_16x16x32_bf16 v[118:121], v[178:181], v[174:177], v[118:121]
	v_add_f32_e32 v251, v103, v251
	v_add_f32_e32 v251, v104, v251
	s_waitcnt lgkmcnt(8)
	v_mfma_f32_16x16x32_bf16 v[122:125], v[182:185], v[158:161], v[122:125]
	v_add_f32_e32 v251, v105, v251
	ds_read_b64_tr_b16 v[214:215], v241 offset:0
	ds_read_b64_tr_b16 v[216:217], v241 offset:4096
	v_mfma_f32_16x16x32_bf16 v[126:129], v[182:185], v[174:177], v[126:129]
	v_add_f32_e32 v251, v110, v251
	v_add_f32_e32 v251, v111, v251
	s_waitcnt lgkmcnt(7)
	v_mfma_f32_16x16x32_bf16 v[130:133], v[186:189], v[158:161], v[130:133]
	v_add_f32_e32 v251, v112, v251
	ds_read_b64_tr_b16 v[218:219], v242 offset:0
	ds_read_b64_tr_b16 v[220:221], v242 offset:4096
	v_mfma_f32_16x16x32_bf16 v[134:137], v[186:189], v[174:177], v[134:137]
	v_add_f32_e32 v251, v113, v251
	v_cvt_pk_bf16_f32 v102, v102, v103
	s_waitcnt lgkmcnt(6)
; #define SBAR() __builtin_amdgcn_sched_barrier(0)
; template <int D0> __device__ __forceinline__ void pv_one(f32x16& od, int vb, bf16x8 pa0, bf16x8 pa1, bf16x8 pa2, bf16x8 pa3) {
;   const s16x4 l0 = tr_read<v_rd_off(D0, 0, 0)>(vb), h0 = tr_read<v_rd_off(D0, 0, 1)>(vb), l1 = tr_read<v_rd_off(D0, 1, 0)>(vb), h1 = tr_read<v_rd_off(D0, 1, 1)>(vb);
;   const s16x4 l2 = tr_read<v_rd_off(D0, 2, 0)>(vb), h2 = tr_read<v_rd_off(D0, 2, 1)>(vb), l3 = tr_read<v_rd_off(D0, 3, 0)>(vb), h3 = tr_read<v_rd_off(D0, 3, 1)>(vb);
;   asm volatile("s_waitcnt lgkmcnt(0)" ::: "memory"); SBAR();
;     ...
;   od = __builtin_amdgcn_mfma_f32_32x32x16_bf16(pa0, PK(l0, h0), od, 0, 0, 0);
;   od = __builtin_amdgcn_mfma_f32_32x32x16_bf16(pa1, PK(l1, h1), od, 0, 0, 0);
;   od = __builtin_amdgcn_mfma_f32_32x32x16_bf16(pa2, PK(l2, h2), od, 0, 0, 0);
;   od = __builtin_amdgcn_mfma_f32_32x32x16_bf16(pa3, PK(l3, h3), od, 0, 0, 0);
;     ...
; }
; __device__ __forceinline__ void pv_d0(f32x16* o, int vb, bf16x8 pa0, bf16x8 pa1, bf16x8 pa2, bf16x8 pa3) {
;   pv_one<0>(o[0], vb, pa0, pa1, pa2, pa3); pv_one<1>(o[1], vb, pa0, pa1, pa2, pa3); pv_one<2>(o[2], vb, pa0, pa1, pa2, pa3); pv_one<3>(o[3], vb, pa0, pa1, pa2, pa3);
; template <typename TQ> ...
;     ...
;   SBAR(); qkt(pB0, pB1, (bf16*)((char*)K_lds + SHM_K), qr, r32, hi, negm);
;   finishSM(pA0, pA1, l_reg, pa0, pa1, pa2, pa3); SBAR();
;   pv_d0(o, vb0, pa0, pa1, pa2, pa3); partialSM(pB0, pB1, mC);
;   __syncthreads();
	v_mfma_f32_16x16x32_bf16 v[138:141], v[190:193], v[158:161], v[138:141]
	v_cvt_pk_bf16_f32 v103, v104, v105
	ds_read_b64_tr_b16 v[222:223], v243 offset:0
	ds_read_b64_tr_b16 v[224:225], v243 offset:4096
	v_mfma_f32_16x16x32_bf16 v[142:145], v[190:193], v[174:177], v[142:145]
	v_cvt_pk_bf16_f32 v104, v110, v111
	v_cvt_pk_bf16_f32 v105, v112, v113
	v_mfma_f32_16x16x32_bf16 v[18:21], v[202:205], v[82:85], v[18:21]
	v_exp_f32_e32 v114, v114
	v_mfma_f32_16x16x32_bf16 v[22:25], v[202:205], v[86:89], v[22:25]
	ds_read_b64_tr_b16 v[202:203], v244 offset:0
	ds_read_b64_tr_b16 v[204:205], v244 offset:4096
	v_exp_f32_e32 v115, v115
	v_mfma_f32_16x16x32_bf16 v[26:29], v[206:209], v[82:85], v[26:29]
	v_exp_f32_e32 v116, v116
	v_mfma_f32_16x16x32_bf16 v[30:33], v[206:209], v[86:89], v[30:33]
	ds_read_b64_tr_b16 v[206:207], v245 offset:0
	ds_read_b64_tr_b16 v[208:209], v245 offset:4096
	v_exp_f32_e32 v117, v117
	s_waitcnt lgkmcnt(10)
	v_mfma_f32_16x16x32_bf16 v[34:37], v[210:213], v[82:85], v[34:37]
	v_exp_f32_e32 v118, v118
	v_mfma_f32_16x16x32_bf16 v[38:41], v[210:213], v[86:89], v[38:41]
	ds_read_b64_tr_b16 v[210:211], v238 offset:8192
	ds_read_b64_tr_b16 v[212:213], v238 offset:12288
	v_exp_f32_e32 v119, v119
	s_waitcnt lgkmcnt(10)
	v_mfma_f32_16x16x32_bf16 v[42:45], v[214:217], v[82:85], v[42:45]
	v_exp_f32_e32 v120, v120
	v_mfma_f32_16x16x32_bf16 v[46:49], v[214:217], v[86:89], v[46:49]
	ds_read_b64_tr_b16 v[214:215], v239 offset:8192
	ds_read_b64_tr_b16 v[216:217], v239 offset:12288
	v_exp_f32_e32 v121, v121
	s_waitcnt lgkmcnt(10)
	v_mfma_f32_16x16x32_bf16 v[50:53], v[218:221], v[82:85], v[50:53]
	v_exp_f32_e32 v122, v122
	v_mfma_f32_16x16x32_bf16 v[54:57], v[218:221], v[86:89], v[54:57]
	ds_read_b64_tr_b16 v[218:219], v240 offset:8192
	ds_read_b64_tr_b16 v[220:221], v240 offset:12288
	v_exp_f32_e32 v123, v123
	s_waitcnt lgkmcnt(10)
	v_mfma_f32_16x16x32_bf16 v[58:61], v[222:225], v[82:85], v[58:61]
	v_exp_f32_e32 v124, v124
	v_mfma_f32_16x16x32_bf16 v[62:65], v[222:225], v[86:89], v[62:65]
	ds_read_b64_tr_b16 v[222:223], v241 offset:8192
	ds_read_b64_tr_b16 v[224:225], v241 offset:12288
	v_exp_f32_e32 v125, v125
	s_waitcnt lgkmcnt(10)
	v_mfma_f32_16x16x32_bf16 v[66:69], v[202:205], v[82:85], v[66:69]
	v_exp_f32_e32 v126, v126
	v_mfma_f32_16x16x32_bf16 v[70:73], v[202:205], v[86:89], v[70:73]
	ds_read_b64_tr_b16 v[202:203], v242 offset:8192
	ds_read_b64_tr_b16 v[204:205], v242 offset:12288
	v_exp_f32_e32 v127, v127
	s_waitcnt lgkmcnt(10)
	v_mfma_f32_16x16x32_bf16 v[74:77], v[206:209], v[82:85], v[74:77]
	v_exp_f32_e32 v128, v128
	v_mfma_f32_16x16x32_bf16 v[78:81], v[206:209], v[86:89], v[78:81]
	ds_read_b64_tr_b16 v[206:207], v243 offset:8192
	ds_read_b64_tr_b16 v[208:209], v243 offset:12288
	v_exp_f32_e32 v129, v129
	s_waitcnt lgkmcnt(10)
	v_mfma_f32_16x16x32_bf16 v[18:21], v[210:213], v[98:101], v[18:21]
	v_exp_f32_e32 v130, v130
	v_mfma_f32_16x16x32_bf16 v[22:25], v[210:213], v[102:105], v[22:25]
	ds_read_b64_tr_b16 v[210:211], v244 offset:8192
	ds_read_b64_tr_b16 v[212:213], v244 offset:12288
	v_exp_f32_e32 v131, v131
	s_waitcnt lgkmcnt(10)
	v_mfma_f32_16x16x32_bf16 v[26:29], v[214:217], v[98:101], v[26:29]
	v_exp_f32_e32 v132, v132
	v_mfma_f32_16x16x32_bf16 v[30:33], v[214:217], v[102:105], v[30:33]
	ds_read_b64_tr_b16 v[214:215], v245 offset:8192
	ds_read_b64_tr_b16 v[216:217], v245 offset:12288
	v_exp_f32_e32 v133, v133
	s_waitcnt lgkmcnt(10)
	v_mfma_f32_16x16x32_bf16 v[34:37], v[218:221], v[98:101], v[34:37]
	v_exp_f32_e32 v134, v134
	v_mfma_f32_16x16x32_bf16 v[38:41], v[218:221], v[102:105], v[38:41]
	v_exp_f32_e32 v135, v135
	s_waitcnt lgkmcnt(8)
	v_mfma_f32_16x16x32_bf16 v[42:45], v[222:225], v[98:101], v[42:45]
	v_exp_f32_e32 v136, v136
	v_mfma_f32_16x16x32_bf16 v[46:49], v[222:225], v[102:105], v[46:49]
	v_exp_f32_e32 v137, v137
	s_waitcnt lgkmcnt(6)
	v_mfma_f32_16x16x32_bf16 v[50:53], v[202:205], v[98:101], v[50:53]
	v_exp_f32_e32 v138, v138
	ds_read_b128 v[178:181], v234 offset:32768
	v_mfma_f32_16x16x32_bf16 v[54:57], v[202:205], v[102:105], v[54:57]
	v_exp_f32_e32 v139, v139
	s_waitcnt lgkmcnt(5)
	v_mfma_f32_16x16x32_bf16 v[58:61], v[206:209], v[98:101], v[58:61]
	v_exp_f32_e32 v140, v140
	ds_read_b128 v[182:185], v234 offset:36864
	v_mfma_f32_16x16x32_bf16 v[62:65], v[206:209], v[102:105], v[62:65]
	v_exp_f32_e32 v141, v141
	s_waitcnt lgkmcnt(4)
	v_mfma_f32_16x16x32_bf16 v[66:69], v[210:213], v[98:101], v[66:69]
	v_exp_f32_e32 v142, v142
	ds_read_b128 v[186:189], v234 offset:40960
	v_mfma_f32_16x16x32_bf16 v[70:73], v[210:213], v[102:105], v[70:73]
	v_exp_f32_e32 v143, v143
	s_waitcnt lgkmcnt(3)
	v_mfma_f32_16x16x32_bf16 v[74:77], v[214:217], v[98:101], v[74:77]
	v_exp_f32_e32 v144, v144
	ds_read_b128 v[190:193], v234 offset:45056
	v_mfma_f32_16x16x32_bf16 v[78:81], v[214:217], v[102:105], v[78:81]
	v_exp_f32_e32 v145, v145
	s_waitcnt vmcnt(2)
	s_barrier
; #define SBAR() __builtin_amdgcn_sched_barrier(0)
; __device__ __forceinline__ void finishSM(f32x16& p0, f32x16& p1, float& l_reg, bf16x8& pa0, bf16x8& pa1, bf16x8& pa2, bf16x8& pa3) {
;   for (int r = 0; r < 16; ++r) p1[r] = __builtin_amdgcn_exp2f(p1[r]);
;   float ps = 0; for (int r = 0; r < 16; ++r) ps += p0[r]; for (int r = 0; r < 16; ++r) ps += p1[r];
;   { auto rr = __builtin_amdgcn_permlane32_swap(__float_as_uint(ps), __float_as_uint(ps), false, false);
;     ps = __uint_as_float(rr[0]) + __uint_as_float(rr[1]); }
;   l_reg += ps;
;     ...
;   PK4(p0, 0, pa0); PK4(p0, 8, pa1); PK4(p1, 0, pa2); PK4(p1, 8, pa3);
;     ...
; }
; __device__ __forceinline__ void qkt(f32x16& p0, f32x16& p1, const bf16* Ks, const bf16x8* qr, int r32, int hi, const f32x16& negm) {
; #pragma unroll
;   for (int d0 = 0; d0 < 8; ++d0) { int cb = (d0 * 16 + hi * 8) * 2;
;     bf16x8 b0 = *reinterpret_cast<const bf16x8*>((const char*)Ks + KSWZ(r32, cb));
;     bf16x8 b1 = *reinterpret_cast<const bf16x8*>((const char*)Ks + KSWZ(32 + r32, cb));
;     if (d0 == 0) { p0 = __builtin_amdgcn_mfma_f32_32x32x16_bf16(b0, qr[0], negm, 0, 0, 0); p1 = __builtin_amdgcn_mfma_f32_32x32x16_bf16(b1, qr[0], negm, 0, 0, 0); }
;     else { p0 = __builtin_amdgcn_mfma_f32_32x32x16_bf16(b0, qr[d0], p0, 0, 0, 0); p1 = __builtin_amdgcn_mfma_f32_32x32x16_bf16(b1, qr[d0], p1, 0, 0, 0); } }
; }
; template <typename TQ> ...
;     ...
;   SBAR(); qkt(pB0, pB1, (bf16*)((char*)K_lds + SHM_K), qr, r32, hi, negm);
;   finishSM(pA0, pA1, l_reg, pa0, pa1, pa2, pa3); SBAR();
;   pv_d0(o, vb0, pa0, pa1, pa2, pa3); partialSM(pB0, pB1, mC);
;   __syncthreads();
;   finishSM(pB0, pB1, l_reg, pa0, pa1, pa2, pa3); SBAR();
	s_waitcnt lgkmcnt(3)
	v_mfma_f32_16x16x32_bf16 v[82:85], v[178:181], v[146:149], v[2:5]
	v_add_f32_e32 v250, v114, v250
	v_mfma_f32_16x16x32_bf16 v[86:89], v[178:181], v[162:165], v[2:5]
	ds_read_b128 v[178:181], v235 offset:32768
	v_add_f32_e32 v250, v115, v250
	v_add_f32_e32 v250, v116, v250
	s_waitcnt lgkmcnt(3)
	v_mfma_f32_16x16x32_bf16 v[90:93], v[182:185], v[146:149], v[2:5]
	v_add_f32_e32 v250, v117, v250
	v_mfma_f32_16x16x32_bf16 v[94:97], v[182:185], v[162:165], v[2:5]
	ds_read_b128 v[182:185], v235 offset:36864
	v_add_f32_e32 v250, v122, v250
	v_add_f32_e32 v250, v123, v250
	s_waitcnt lgkmcnt(3)
	v_mfma_f32_16x16x32_bf16 v[98:101], v[186:189], v[146:149], v[2:5]
	v_add_f32_e32 v250, v124, v250
	v_mfma_f32_16x16x32_bf16 v[102:105], v[186:189], v[162:165], v[2:5]
	ds_read_b128 v[186:189], v235 offset:40960
	v_add_f32_e32 v250, v125, v250
	v_cvt_pk_bf16_f32 v114, v114, v115
	s_waitcnt lgkmcnt(3)
	v_mfma_f32_16x16x32_bf16 v[106:109], v[190:193], v[146:149], v[2:5]
	v_cvt_pk_bf16_f32 v115, v116, v117
	v_mfma_f32_16x16x32_bf16 v[110:113], v[190:193], v[162:165], v[2:5]
	ds_read_b128 v[190:193], v235 offset:45056
	v_cvt_pk_bf16_f32 v116, v122, v123
	v_cvt_pk_bf16_f32 v117, v124, v125
	s_waitcnt lgkmcnt(3)
	v_mfma_f32_16x16x32_bf16 v[82:85], v[178:181], v[150:153], v[82:85]
	v_add_f32_e32 v251, v118, v251
	v_mfma_f32_16x16x32_bf16 v[86:89], v[178:181], v[166:169], v[86:89]
	ds_read_b128 v[178:181], v236 offset:32768
	v_add_f32_e32 v251, v119, v251
	v_add_f32_e32 v251, v120, v251
	s_waitcnt lgkmcnt(3)
	v_mfma_f32_16x16x32_bf16 v[90:93], v[182:185], v[150:153], v[90:93]
	v_add_f32_e32 v251, v121, v251
	v_mfma_f32_16x16x32_bf16 v[94:97], v[182:185], v[166:169], v[94:97]
	ds_read_b128 v[182:185], v236 offset:36864
	v_add_f32_e32 v251, v126, v251
	v_add_f32_e32 v251, v127, v251
	s_waitcnt lgkmcnt(3)
	v_mfma_f32_16x16x32_bf16 v[98:101], v[186:189], v[150:153], v[98:101]
	v_add_f32_e32 v251, v128, v251
	v_mfma_f32_16x16x32_bf16 v[102:105], v[186:189], v[166:169], v[102:105]
	ds_read_b128 v[186:189], v236 offset:40960
	v_add_f32_e32 v251, v129, v251
	v_cvt_pk_bf16_f32 v118, v118, v119
	s_waitcnt lgkmcnt(3)
	v_mfma_f32_16x16x32_bf16 v[106:109], v[190:193], v[150:153], v[106:109]
	v_cvt_pk_bf16_f32 v119, v120, v121
	v_mfma_f32_16x16x32_bf16 v[110:113], v[190:193], v[166:169], v[110:113]
	ds_read_b128 v[190:193], v236 offset:45056
	v_cvt_pk_bf16_f32 v120, v126, v127
	v_cvt_pk_bf16_f32 v121, v128, v129
	s_waitcnt lgkmcnt(3)
	v_mfma_f32_16x16x32_bf16 v[82:85], v[178:181], v[154:157], v[82:85]
	v_add_f32_e32 v250, v130, v250
	v_mfma_f32_16x16x32_bf16 v[86:89], v[178:181], v[170:173], v[86:89]
	ds_read_b128 v[178:181], v237 offset:32768
	v_add_f32_e32 v250, v131, v250
	v_add_f32_e32 v250, v132, v250
	s_waitcnt lgkmcnt(3)
	v_mfma_f32_16x16x32_bf16 v[90:93], v[182:185], v[154:157], v[90:93]
	v_add_f32_e32 v250, v133, v250
	v_mfma_f32_16x16x32_bf16 v[94:97], v[182:185], v[170:173], v[94:97]
	ds_read_b128 v[182:185], v237 offset:36864
	v_add_f32_e32 v250, v138, v250
	v_add_f32_e32 v250, v139, v250
	s_waitcnt lgkmcnt(3)
	v_mfma_f32_16x16x32_bf16 v[98:101], v[186:189], v[154:157], v[98:101]
	v_add_f32_e32 v250, v140, v250
	ds_read_b64_tr_b16 v[202:203], v238 offset:16384
	ds_read_b64_tr_b16 v[204:205], v238 offset:20480
	v_mfma_f32_16x16x32_bf16 v[102:105], v[186:189], v[170:173], v[102:105]
	ds_read_b128 v[186:189], v237 offset:40960
	v_add_f32_e32 v250, v141, v250
	v_cvt_pk_bf16_f32 v130, v130, v131
	s_waitcnt lgkmcnt(5)
	v_mfma_f32_16x16x32_bf16 v[106:109], v[190:193], v[154:157], v[106:109]
	v_cvt_pk_bf16_f32 v131, v132, v133
	ds_read_b64_tr_b16 v[206:207], v239 offset:16384
	ds_read_b64_tr_b16 v[208:209], v239 offset:20480
	v_mfma_f32_16x16x32_bf16 v[110:113], v[190:193], v[170:173], v[110:113]
	ds_read_b128 v[190:193], v237 offset:45056
	v_cvt_pk_bf16_f32 v132, v138, v139
	v_cvt_pk_bf16_f32 v133, v140, v141
	s_waitcnt lgkmcnt(7)
	v_mfma_f32_16x16x32_bf16 v[82:85], v[178:181], v[158:161], v[82:85]
	v_add_f32_e32 v251, v134, v251
	ds_read_b64_tr_b16 v[210:211], v240 offset:16384
	ds_read_b64_tr_b16 v[212:213], v240 offset:20480
	v_mfma_f32_16x16x32_bf16 v[86:89], v[178:181], v[174:177], v[86:89]
	v_add_f32_e32 v251, v135, v251
	v_add_f32_e32 v251, v136, v251
	s_waitcnt lgkmcnt(8)
	v_mfma_f32_16x16x32_bf16 v[90:93], v[182:185], v[158:161], v[90:93]
	v_add_f32_e32 v251, v137, v251
	ds_read_b64_tr_b16 v[214:215], v241 offset:16384
	ds_read_b64_tr_b16 v[216:217], v241 offset:20480
	v_mfma_f32_16x16x32_bf16 v[94:97], v[182:185], v[174:177], v[94:97]
	v_add_f32_e32 v251, v142, v251
	v_add_f32_e32 v251, v143, v251
	s_waitcnt lgkmcnt(7)
	v_mfma_f32_16x16x32_bf16 v[98:101], v[186:189], v[158:161], v[98:101]
	v_add_f32_e32 v251, v144, v251
	ds_read_b64_tr_b16 v[218:219], v242 offset:16384
	ds_read_b64_tr_b16 v[220:221], v242 offset:20480
	v_mfma_f32_16x16x32_bf16 v[102:105], v[186:189], v[174:177], v[102:105]
	v_add_f32_e32 v251, v145, v251
	v_cvt_pk_bf16_f32 v134, v134, v135
	s_waitcnt lgkmcnt(6)
	v_mfma_f32_16x16x32_bf16 v[106:109], v[190:193], v[158:161], v[106:109]
	v_cvt_pk_bf16_f32 v135, v136, v137
	ds_read_b64_tr_b16 v[222:223], v243 offset:16384
	ds_read_b64_tr_b16 v[224:225], v243 offset:20480
	v_mfma_f32_16x16x32_bf16 v[110:113], v[190:193], v[174:177], v[110:113]
	v_cvt_pk_bf16_f32 v136, v142, v143
	v_cvt_pk_bf16_f32 v137, v144, v145
	v_mfma_f32_16x16x32_bf16 v[18:21], v[202:205], v[114:117], v[18:21]
	v_exp_f32_e32 v82, v82
	v_mfma_f32_16x16x32_bf16 v[22:25], v[202:205], v[118:121], v[22:25]
	ds_read_b64_tr_b16 v[202:203], v244 offset:16384
	ds_read_b64_tr_b16 v[204:205], v244 offset:20480
	v_exp_f32_e32 v83, v83
	v_mfma_f32_16x16x32_bf16 v[26:29], v[206:209], v[114:117], v[26:29]
	v_exp_f32_e32 v84, v84
	v_mfma_f32_16x16x32_bf16 v[30:33], v[206:209], v[118:121], v[30:33]
	ds_read_b64_tr_b16 v[206:207], v245 offset:16384
	ds_read_b64_tr_b16 v[208:209], v245 offset:20480
	v_exp_f32_e32 v85, v85
	s_waitcnt lgkmcnt(10)
; __device__ __forceinline__ void partialSM(f32x16& p0, f32x16& p1, float mC) {
;     ...
;   for (int r = 0; r < 16; ++r) p0[r] = __builtin_amdgcn_exp2f(p0[r]);
; }
; __device__ __forceinline__ void finishSM(f32x16& p0, f32x16& p1, float& l_reg, bf16x8& pa0, bf16x8& pa1, bf16x8& pa2, bf16x8& pa3) {
;   for (int r = 0; r < 16; ++r) p1[r] = __builtin_amdgcn_exp2f(p1[r]);
;   float ps = 0; for (int r = 0; r < 16; ++r) ps += p0[r]; for (int r = 0; r < 16; ++r) ps += p1[r];
;   { auto rr = __builtin_amdgcn_permlane32_swap(__float_as_uint(ps), __float_as_uint(ps), false, false);
;     ps = __uint_as_float(rr[0]) + __uint_as_float(rr[1]); }
;   l_reg += ps;
;     ...
;   PK4(p0, 0, pa0); PK4(p0, 8, pa1); PK4(p1, 0, pa2); PK4(p1, 8, pa3);
;     ...
; }
; __device__ __forceinline__ void qkt(f32x16& p0, f32x16& p1, const bf16* Ks, const bf16x8* qr, int r32, int hi, const f32x16& negm) {
; #pragma unroll
;   for (int d0 = 0; d0 < 8; ++d0) { int cb = (d0 * 16 + hi * 8) * 2;
;     bf16x8 b0 = *reinterpret_cast<const bf16x8*>((const char*)Ks + KSWZ(r32, cb));
;     bf16x8 b1 = *reinterpret_cast<const bf16x8*>((const char*)Ks + KSWZ(32 + r32, cb));
;     if (d0 == 0) { p0 = __builtin_amdgcn_mfma_f32_32x32x16_bf16(b0, qr[0], negm, 0, 0, 0); p1 = __builtin_amdgcn_mfma_f32_32x32x16_bf16(b1, qr[0], negm, 0, 0, 0); }
;     else { p0 = __builtin_amdgcn_mfma_f32_32x32x16_bf16(b0, qr[d0], p0, 0, 0, 0); p1 = __builtin_amdgcn_mfma_f32_32x32x16_bf16(b1, qr[d0], p1, 0, 0, 0); } }
; }
; __device__ __forceinline__ int v_st(int k, int c) { const int kk = (k & ~0xC) | ((k & 4) << 1) | ((k & 8) >> 1); return ((kk >> 3) * 4 + (c >> 5)) * 512 + ((kk & 7) * 32 + (c & 31)) * 2; }
; __device__ __forceinline__ int v_rd_base(int lane) { return ((lane & 3) << 3) | (((lane >> 2) & 3) << 6) | (((lane >> 4) & 1) << 5) | (((lane >> 5) & 1) << 8); }
; template <int OFF> __device__ __forceinline__ s16x4 tr_read(int vb) {
;   s16x4 r; asm volatile("ds_read_b64_tr_b16 %0, %1 offset:%2" : "=&v"(r) : "v"(vb), "i"(OFF) : "memory"); return r;
; }
; template <int D0> __device__ __forceinline__ void pv_one(f32x16& od, int vb, bf16x8 pa0, bf16x8 pa1, bf16x8 pa2, bf16x8 pa3) {
;   const s16x4 l0 = tr_read<v_rd_off(D0, 0, 0)>(vb), h0 = tr_read<v_rd_off(D0, 0, 1)>(vb), l1 = tr_read<v_rd_off(D0, 1, 0)>(vb), h1 = tr_read<v_rd_off(D0, 1, 1)>(vb);
	v_mfma_f32_16x16x32_bf16 v[34:37], v[210:213], v[114:117], v[34:37]
	v_exp_f32_e32 v86, v86
	v_mfma_f32_16x16x32_bf16 v[38:41], v[210:213], v[118:121], v[38:41]
	ds_read_b64_tr_b16 v[210:211], v238 offset:24576
	ds_read_b64_tr_b16 v[212:213], v238 offset:28672
	v_exp_f32_e32 v87, v87
	s_waitcnt lgkmcnt(10)
	v_mfma_f32_16x16x32_bf16 v[42:45], v[214:217], v[114:117], v[42:45]
	v_exp_f32_e32 v88, v88
	v_mfma_f32_16x16x32_bf16 v[46:49], v[214:217], v[118:121], v[46:49]
	ds_read_b64_tr_b16 v[214:215], v239 offset:24576
	ds_read_b64_tr_b16 v[216:217], v239 offset:28672
	v_exp_f32_e32 v89, v89
	s_waitcnt lgkmcnt(10)
	v_mfma_f32_16x16x32_bf16 v[50:53], v[218:221], v[114:117], v[50:53]
	v_exp_f32_e32 v90, v90
	v_mfma_f32_16x16x32_bf16 v[54:57], v[218:221], v[118:121], v[54:57]
	ds_read_b64_tr_b16 v[218:219], v240 offset:24576
	ds_read_b64_tr_b16 v[220:221], v240 offset:28672
	v_exp_f32_e32 v91, v91
	s_waitcnt lgkmcnt(10)
	v_mfma_f32_16x16x32_bf16 v[58:61], v[222:225], v[114:117], v[58:61]
	v_exp_f32_e32 v92, v92
	v_mfma_f32_16x16x32_bf16 v[62:65], v[222:225], v[118:121], v[62:65]
	ds_read_b64_tr_b16 v[222:223], v241 offset:24576
	ds_read_b64_tr_b16 v[224:225], v241 offset:28672
	v_exp_f32_e32 v93, v93
	s_waitcnt lgkmcnt(10)
	v_mfma_f32_16x16x32_bf16 v[66:69], v[202:205], v[114:117], v[66:69]
	v_exp_f32_e32 v94, v94
	v_mfma_f32_16x16x32_bf16 v[70:73], v[202:205], v[118:121], v[70:73]
	ds_read_b64_tr_b16 v[202:203], v242 offset:24576
	ds_read_b64_tr_b16 v[204:205], v242 offset:28672
	v_exp_f32_e32 v95, v95
	s_waitcnt lgkmcnt(10)
	v_mfma_f32_16x16x32_bf16 v[74:77], v[206:209], v[114:117], v[74:77]
	v_exp_f32_e32 v96, v96
	v_mfma_f32_16x16x32_bf16 v[78:81], v[206:209], v[118:121], v[78:81]
	ds_read_b64_tr_b16 v[206:207], v243 offset:24576
	ds_read_b64_tr_b16 v[208:209], v243 offset:28672
	v_exp_f32_e32 v97, v97
	s_waitcnt lgkmcnt(10)
	v_mfma_f32_16x16x32_bf16 v[18:21], v[210:213], v[130:133], v[18:21]
	v_exp_f32_e32 v98, v98
	v_mfma_f32_16x16x32_bf16 v[22:25], v[210:213], v[134:137], v[22:25]
	ds_read_b64_tr_b16 v[210:211], v244 offset:24576
	ds_read_b64_tr_b16 v[212:213], v244 offset:28672
	v_exp_f32_e32 v99, v99
	s_waitcnt lgkmcnt(10)
	v_mfma_f32_16x16x32_bf16 v[26:29], v[214:217], v[130:133], v[26:29]
	v_exp_f32_e32 v100, v100
	v_mfma_f32_16x16x32_bf16 v[30:33], v[214:217], v[134:137], v[30:33]
	ds_read_b64_tr_b16 v[214:215], v245 offset:24576
	ds_read_b64_tr_b16 v[216:217], v245 offset:28672
	v_exp_f32_e32 v101, v101
	s_waitcnt lgkmcnt(10)
	v_mfma_f32_16x16x32_bf16 v[34:37], v[218:221], v[130:133], v[34:37]
	v_exp_f32_e32 v102, v102
	v_mfma_f32_16x16x32_bf16 v[38:41], v[218:221], v[134:137], v[38:41]
	v_exp_f32_e32 v103, v103
	s_waitcnt lgkmcnt(8)
	v_mfma_f32_16x16x32_bf16 v[42:45], v[222:225], v[130:133], v[42:45]
	v_exp_f32_e32 v104, v104
	v_mfma_f32_16x16x32_bf16 v[46:49], v[222:225], v[134:137], v[46:49]
	v_exp_f32_e32 v105, v105
	s_waitcnt lgkmcnt(6)
	v_mfma_f32_16x16x32_bf16 v[50:53], v[202:205], v[130:133], v[50:53]
	v_exp_f32_e32 v106, v106
	ds_read_b128 v[178:181], v234 offset:49152
	v_mfma_f32_16x16x32_bf16 v[54:57], v[202:205], v[134:137], v[54:57]
	v_exp_f32_e32 v107, v107
	s_waitcnt lgkmcnt(5)
	v_mfma_f32_16x16x32_bf16 v[58:61], v[206:209], v[130:133], v[58:61]
	v_exp_f32_e32 v108, v108
	ds_read_b128 v[182:185], v234 offset:53248
	v_mfma_f32_16x16x32_bf16 v[62:65], v[206:209], v[134:137], v[62:65]
	v_exp_f32_e32 v109, v109
	s_waitcnt lgkmcnt(4)
	v_mfma_f32_16x16x32_bf16 v[66:69], v[210:213], v[130:133], v[66:69]
	v_exp_f32_e32 v110, v110
	ds_read_b128 v[186:189], v234 offset:57344
	v_mfma_f32_16x16x32_bf16 v[70:73], v[210:213], v[134:137], v[70:73]
	v_exp_f32_e32 v111, v111
	s_waitcnt lgkmcnt(3)
	v_mfma_f32_16x16x32_bf16 v[74:77], v[214:217], v[130:133], v[74:77]
	v_exp_f32_e32 v112, v112
	ds_read_b128 v[190:193], v234 offset:61440
	v_mfma_f32_16x16x32_bf16 v[78:81], v[214:217], v[134:137], v[78:81]
	v_exp_f32_e32 v113, v113
	s_waitcnt vmcnt(0)
	s_barrier
	s_waitcnt lgkmcnt(3)
	v_mfma_f32_16x16x32_bf16 v[114:117], v[178:181], v[146:149], v[2:5]
	v_add_f32_e32 v250, v82, v250
	v_mfma_f32_16x16x32_bf16 v[118:121], v[178:181], v[162:165], v[2:5]
	ds_read_b128 v[178:181], v235 offset:49152
	v_add_f32_e32 v250, v83, v250
	v_add_f32_e32 v250, v84, v250
	s_waitcnt lgkmcnt(3)
	v_mfma_f32_16x16x32_bf16 v[122:125], v[182:185], v[146:149], v[2:5]
	v_add_f32_e32 v250, v85, v250
	v_mfma_f32_16x16x32_bf16 v[126:129], v[182:185], v[162:165], v[2:5]
	ds_read_b128 v[182:185], v235 offset:53248
	v_add_f32_e32 v250, v90, v250
	v_add_f32_e32 v250, v91, v250
	s_waitcnt lgkmcnt(3)
	v_mfma_f32_16x16x32_bf16 v[130:133], v[186:189], v[146:149], v[2:5]
	v_add_f32_e32 v250, v92, v250
	v_mfma_f32_16x16x32_bf16 v[134:137], v[186:189], v[162:165], v[2:5]
	ds_read_b128 v[186:189], v235 offset:57344
	v_add_f32_e32 v250, v93, v250
	v_cvt_pk_bf16_f32 v82, v82, v83
	s_waitcnt lgkmcnt(3)
	v_mfma_f32_16x16x32_bf16 v[138:141], v[190:193], v[146:149], v[2:5]
	v_cvt_pk_bf16_f32 v83, v84, v85
	v_mfma_f32_16x16x32_bf16 v[142:145], v[190:193], v[162:165], v[2:5]
	ds_read_b128 v[190:193], v235 offset:61440
	v_cvt_pk_bf16_f32 v84, v90, v91
	v_cvt_pk_bf16_f32 v85, v92, v93
	s_waitcnt lgkmcnt(3)
	v_mfma_f32_16x16x32_bf16 v[114:117], v[178:181], v[150:153], v[114:117]
	v_add_f32_e32 v251, v86, v251
	v_mfma_f32_16x16x32_bf16 v[118:121], v[178:181], v[166:169], v[118:121]
	ds_read_b128 v[178:181], v236 offset:49152
	v_add_f32_e32 v251, v87, v251
	v_add_f32_e32 v251, v88, v251
	s_waitcnt lgkmcnt(3)
	v_mfma_f32_16x16x32_bf16 v[122:125], v[182:185], v[150:153], v[122:125]
	v_add_f32_e32 v251, v89, v251
	v_mfma_f32_16x16x32_bf16 v[126:129], v[182:185], v[166:169], v[126:129]
	ds_read_b128 v[182:185], v236 offset:53248
	v_add_f32_e32 v251, v94, v251
	v_add_f32_e32 v251, v95, v251
	s_waitcnt lgkmcnt(3)
; __device__ __forceinline__ void partialSM(f32x16& p0, f32x16& p1, float mC) {
;     ...
;   for (int r = 0; r < 16; ++r) p0[r] = __builtin_amdgcn_exp2f(p0[r]);
; }
; __device__ __forceinline__ void finishSM(f32x16& p0, f32x16& p1, float& l_reg, bf16x8& pa0, bf16x8& pa1, bf16x8& pa2, bf16x8& pa3) {
;   for (int r = 0; r < 16; ++r) p1[r] = __builtin_amdgcn_exp2f(p1[r]);
;   float ps = 0; for (int r = 0; r < 16; ++r) ps += p0[r]; for (int r = 0; r < 16; ++r) ps += p1[r];
;   { auto rr = __builtin_amdgcn_permlane32_swap(__float_as_uint(ps), __float_as_uint(ps), false, false);
;     ps = __uint_as_float(rr[0]) + __uint_as_float(rr[1]); }
;   l_reg += ps;
;     ...
;   PK4(p0, 0, pa0); PK4(p0, 8, pa1); PK4(p1, 0, pa2); PK4(p1, 8, pa3);
;     ...
; }
; __device__ __forceinline__ void qkt(f32x16& p0, f32x16& p1, const bf16* Ks, const bf16x8* qr, int r32, int hi, const f32x16& negm) {
; #pragma unroll
;   for (int d0 = 0; d0 < 8; ++d0) { int cb = (d0 * 16 + hi * 8) * 2;
;     bf16x8 b0 = *reinterpret_cast<const bf16x8*>((const char*)Ks + KSWZ(r32, cb));
;     bf16x8 b1 = *reinterpret_cast<const bf16x8*>((const char*)Ks + KSWZ(32 + r32, cb));
;     if (d0 == 0) { p0 = __builtin_amdgcn_mfma_f32_32x32x16_bf16(b0, qr[0], negm, 0, 0, 0); p1 = __builtin_amdgcn_mfma_f32_32x32x16_bf16(b1, qr[0], negm, 0, 0, 0); }
;     else { p0 = __builtin_amdgcn_mfma_f32_32x32x16_bf16(b0, qr[d0], p0, 0, 0, 0); p1 = __builtin_amdgcn_mfma_f32_32x32x16_bf16(b1, qr[d0], p1, 0, 0, 0); } }
; }
; __device__ __forceinline__ int v_st(int k, int c) { const int kk = (k & ~0xC) | ((k & 4) << 1) | ((k & 8) >> 1); return ((kk >> 3) * 4 + (c >> 5)) * 512 + ((kk & 7) * 32 + (c & 31)) * 2; }
; __device__ __forceinline__ int v_rd_base(int lane) { return ((lane & 3) << 3) | (((lane >> 2) & 3) << 6) | (((lane >> 4) & 1) << 5) | (((lane >> 5) & 1) << 8); }
; template <int OFF> __device__ __forceinline__ s16x4 tr_read(int vb) {
;   s16x4 r; asm volatile("ds_read_b64_tr_b16 %0, %1 offset:%2" : "=&v"(r) : "v"(vb), "i"(OFF) : "memory"); return r;
; }
; template <int D0> __device__ __forceinline__ void pv_one(f32x16& od, int vb, bf16x8 pa0, bf16x8 pa1, bf16x8 pa2, bf16x8 pa3) {
;   const s16x4 l0 = tr_read<v_rd_off(D0, 0, 0)>(vb), h0 = tr_read<v_rd_off(D0, 0, 1)>(vb), l1 = tr_read<v_rd_off(D0, 1, 0)>(vb), h1 = tr_read<v_rd_off(D0, 1, 1)>(vb);
	v_mfma_f32_16x16x32_bf16 v[130:133], v[186:189], v[150:153], v[130:133]
	v_add_f32_e32 v251, v96, v251
	v_mfma_f32_16x16x32_bf16 v[134:137], v[186:189], v[166:169], v[134:137]
	ds_read_b128 v[186:189], v236 offset:57344
	v_add_f32_e32 v251, v97, v251
	v_cvt_pk_bf16_f32 v86, v86, v87
	s_waitcnt lgkmcnt(3)
	v_mfma_f32_16x16x32_bf16 v[138:141], v[190:193], v[150:153], v[138:141]
	v_cvt_pk_bf16_f32 v87, v88, v89
	v_mfma_f32_16x16x32_bf16 v[142:145], v[190:193], v[166:169], v[142:145]
	ds_read_b128 v[190:193], v236 offset:61440
	v_cvt_pk_bf16_f32 v88, v94, v95
	v_cvt_pk_bf16_f32 v89, v96, v97
	s_waitcnt lgkmcnt(3)
	v_mfma_f32_16x16x32_bf16 v[114:117], v[178:181], v[154:157], v[114:117]
	v_add_f32_e32 v250, v98, v250
	v_mfma_f32_16x16x32_bf16 v[118:121], v[178:181], v[170:173], v[118:121]
	ds_read_b128 v[178:181], v237 offset:49152
	v_add_f32_e32 v250, v99, v250
	v_add_f32_e32 v250, v100, v250
	s_waitcnt lgkmcnt(3)
	v_mfma_f32_16x16x32_bf16 v[122:125], v[182:185], v[154:157], v[122:125]
	v_add_f32_e32 v250, v101, v250
	v_mfma_f32_16x16x32_bf16 v[126:129], v[182:185], v[170:173], v[126:129]
	ds_read_b128 v[182:185], v237 offset:53248
	v_add_f32_e32 v250, v106, v250
	v_add_f32_e32 v250, v107, v250
	s_waitcnt lgkmcnt(3)
	v_mfma_f32_16x16x32_bf16 v[130:133], v[186:189], v[154:157], v[130:133]
	v_add_f32_e32 v250, v108, v250
	ds_read_b64_tr_b16 v[202:203], v238 offset:32768
	ds_read_b64_tr_b16 v[204:205], v238 offset:36864
	v_mfma_f32_16x16x32_bf16 v[134:137], v[186:189], v[170:173], v[134:137]
	ds_read_b128 v[186:189], v237 offset:57344
	v_add_f32_e32 v250, v109, v250
	v_cvt_pk_bf16_f32 v98, v98, v99
	s_waitcnt lgkmcnt(5)
	v_mfma_f32_16x16x32_bf16 v[138:141], v[190:193], v[154:157], v[138:141]
	v_cvt_pk_bf16_f32 v99, v100, v101
	ds_read_b64_tr_b16 v[206:207], v239 offset:32768
	ds_read_b64_tr_b16 v[208:209], v239 offset:36864
	v_mfma_f32_16x16x32_bf16 v[142:145], v[190:193], v[170:173], v[142:145]
	ds_read_b128 v[190:193], v237 offset:61440
	v_cvt_pk_bf16_f32 v100, v106, v107
	v_cvt_pk_bf16_f32 v101, v108, v109
	s_waitcnt lgkmcnt(7)
	v_mfma_f32_16x16x32_bf16 v[114:117], v[178:181], v[158:161], v[114:117]
	v_add_f32_e32 v251, v102, v251
	ds_read_b64_tr_b16 v[210:211], v240 offset:32768
	ds_read_b64_tr_b16 v[212:213], v240 offset:36864
	v_mfma_f32_16x16x32_bf16 v[118:121], v[178:181], v[174:177], v[118:121]
	v_add_f32_e32 v251, v103, v251
	v_add_f32_e32 v251, v104, v251
	s_waitcnt lgkmcnt(8)
	v_mfma_f32_16x16x32_bf16 v[122:125], v[182:185], v[158:161], v[122:125]
	v_add_f32_e32 v251, v105, v251
	ds_read_b64_tr_b16 v[214:215], v241 offset:32768
	ds_read_b64_tr_b16 v[216:217], v241 offset:36864
	v_mfma_f32_16x16x32_bf16 v[126:129], v[182:185], v[174:177], v[126:129]
	v_add_f32_e32 v251, v110, v251
	v_add_f32_e32 v251, v111, v251
	s_waitcnt lgkmcnt(7)
	v_mfma_f32_16x16x32_bf16 v[130:133], v[186:189], v[158:161], v[130:133]
	v_add_f32_e32 v251, v112, v251
	ds_read_b64_tr_b16 v[218:219], v242 offset:32768
	ds_read_b64_tr_b16 v[220:221], v242 offset:36864
	v_mfma_f32_16x16x32_bf16 v[134:137], v[186:189], v[174:177], v[134:137]
	v_add_f32_e32 v251, v113, v251
	v_cvt_pk_bf16_f32 v102, v102, v103
	s_waitcnt lgkmcnt(6)
	v_mfma_f32_16x16x32_bf16 v[138:141], v[190:193], v[158:161], v[138:141]
	v_cvt_pk_bf16_f32 v103, v104, v105
	ds_read_b64_tr_b16 v[222:223], v243 offset:32768
	ds_read_b64_tr_b16 v[224:225], v243 offset:36864
	v_mfma_f32_16x16x32_bf16 v[142:145], v[190:193], v[174:177], v[142:145]
	v_cvt_pk_bf16_f32 v104, v110, v111
	v_cvt_pk_bf16_f32 v105, v112, v113
	v_mfma_f32_16x16x32_bf16 v[18:21], v[202:205], v[82:85], v[18:21]
	v_exp_f32_e32 v114, v114
	v_mfma_f32_16x16x32_bf16 v[22:25], v[202:205], v[86:89], v[22:25]
	ds_read_b64_tr_b16 v[202:203], v244 offset:32768
	ds_read_b64_tr_b16 v[204:205], v244 offset:36864
	v_exp_f32_e32 v115, v115
	v_mfma_f32_16x16x32_bf16 v[26:29], v[206:209], v[82:85], v[26:29]
	v_exp_f32_e32 v116, v116
	v_mfma_f32_16x16x32_bf16 v[30:33], v[206:209], v[86:89], v[30:33]
	ds_read_b64_tr_b16 v[206:207], v245 offset:32768
	ds_read_b64_tr_b16 v[208:209], v245 offset:36864
	v_exp_f32_e32 v117, v117
	s_waitcnt lgkmcnt(10)
	v_mfma_f32_16x16x32_bf16 v[34:37], v[210:213], v[82:85], v[34:37]
	v_exp_f32_e32 v118, v118
	v_mfma_f32_16x16x32_bf16 v[38:41], v[210:213], v[86:89], v[38:41]
	ds_read_b64_tr_b16 v[210:211], v238 offset:40960
	ds_read_b64_tr_b16 v[212:213], v238 offset:45056
	v_exp_f32_e32 v119, v119
	s_waitcnt lgkmcnt(10)
	v_mfma_f32_16x16x32_bf16 v[42:45], v[214:217], v[82:85], v[42:45]
	v_exp_f32_e32 v120, v120
	v_mfma_f32_16x16x32_bf16 v[46:49], v[214:217], v[86:89], v[46:49]
	ds_read_b64_tr_b16 v[214:215], v239 offset:40960
	ds_read_b64_tr_b16 v[216:217], v239 offset:45056
	v_exp_f32_e32 v121, v121
	s_waitcnt lgkmcnt(10)
	v_mfma_f32_16x16x32_bf16 v[50:53], v[218:221], v[82:85], v[50:53]
	v_exp_f32_e32 v122, v122
	v_mfma_f32_16x16x32_bf16 v[54:57], v[218:221], v[86:89], v[54:57]
	ds_read_b64_tr_b16 v[218:219], v240 offset:40960
	ds_read_b64_tr_b16 v[220:221], v240 offset:45056
	v_exp_f32_e32 v123, v123
	s_waitcnt lgkmcnt(10)
	v_mfma_f32_16x16x32_bf16 v[58:61], v[222:225], v[82:85], v[58:61]
	v_exp_f32_e32 v124, v124
	v_mfma_f32_16x16x32_bf16 v[62:65], v[222:225], v[86:89], v[62:65]
	ds_read_b64_tr_b16 v[222:223], v241 offset:40960
	ds_read_b64_tr_b16 v[224:225], v241 offset:45056
	v_exp_f32_e32 v125, v125
	s_waitcnt lgkmcnt(10)
	v_mfma_f32_16x16x32_bf16 v[66:69], v[202:205], v[82:85], v[66:69]
	v_exp_f32_e32 v126, v126
	v_mfma_f32_16x16x32_bf16 v[70:73], v[202:205], v[86:89], v[70:73]
	ds_read_b64_tr_b16 v[202:203], v242 offset:40960
	ds_read_b64_tr_b16 v[204:205], v242 offset:45056
	v_exp_f32_e32 v127, v127
	s_waitcnt lgkmcnt(10)
; __device__ __forceinline__ void finishSM(f32x16& p0, f32x16& p1, float& l_reg, bf16x8& pa0, bf16x8& pa1, bf16x8& pa2, bf16x8& pa3) {
;   for (int r = 0; r < 16; ++r) p1[r] = __builtin_amdgcn_exp2f(p1[r]);
;   float ps = 0; for (int r = 0; r < 16; ++r) ps += p0[r]; for (int r = 0; r < 16; ++r) ps += p1[r];
;   { auto rr = __builtin_amdgcn_permlane32_swap(__float_as_uint(ps), __float_as_uint(ps), false, false);
;     ps = __uint_as_float(rr[0]) + __uint_as_float(rr[1]); }
;   l_reg += ps;
;     ...
;   PK4(p0, 0, pa0); PK4(p0, 8, pa1); PK4(p1, 0, pa2); PK4(p1, 8, pa3);
;     ...
; }
; __device__ __forceinline__ void qkt(f32x16& p0, f32x16& p1, const bf16* Ks, const bf16x8* qr, int r32, int hi, const f32x16& negm) {
; #pragma unroll
;   for (int d0 = 0; d0 < 8; ++d0) { int cb = (d0 * 16 + hi * 8) * 2;
;     bf16x8 b0 = *reinterpret_cast<const bf16x8*>((const char*)Ks + KSWZ(r32, cb));
;     bf16x8 b1 = *reinterpret_cast<const bf16x8*>((const char*)Ks + KSWZ(32 + r32, cb));
;     if (d0 == 0) { p0 = __builtin_amdgcn_mfma_f32_32x32x16_bf16(b0, qr[0], negm, 0, 0, 0); p1 = __builtin_amdgcn_mfma_f32_32x32x16_bf16(b1, qr[0], negm, 0, 0, 0); }
;     else { p0 = __builtin_amdgcn_mfma_f32_32x32x16_bf16(b0, qr[d0], p0, 0, 0, 0); p1 = __builtin_amdgcn_mfma_f32_32x32x16_bf16(b1, qr[d0], p1, 0, 0, 0); } }
; }
; __device__ __forceinline__ int v_st(int k, int c) { const int kk = (k & ~0xC) | ((k & 4) << 1) | ((k & 8) >> 1); return ((kk >> 3) * 4 + (c >> 5)) * 512 + ((kk & 7) * 32 + (c & 31)) * 2; }
; __device__ __forceinline__ int v_rd_base(int lane) { return ((lane & 3) << 3) | (((lane >> 2) & 3) << 6) | (((lane >> 4) & 1) << 5) | (((lane >> 5) & 1) << 8); }
; template <int OFF> __device__ __forceinline__ s16x4 tr_read(int vb) {
;   s16x4 r; asm volatile("ds_read_b64_tr_b16 %0, %1 offset:%2" : "=&v"(r) : "v"(vb), "i"(OFF) : "memory"); return r;
; }
; template <int D0> __device__ __forceinline__ void pv_one(f32x16& od, int vb, bf16x8 pa0, bf16x8 pa1, bf16x8 pa2, bf16x8 pa3) {
;   const s16x4 l0 = tr_read<v_rd_off(D0, 0, 0)>(vb), h0 = tr_read<v_rd_off(D0, 0, 1)>(vb), l1 = tr_read<v_rd_off(D0, 1, 0)>(vb), h1 = tr_read<v_rd_off(D0, 1, 1)>(vb);
;   const s16x4 l2 = tr_read<v_rd_off(D0, 2, 0)>(vb), h2 = tr_read<v_rd_off(D0, 2, 1)>(vb), l3 = tr_read<v_rd_off(D0, 3, 0)>(vb), h3 = tr_read<v_rd_off(D0, 3, 1)>(vb);
;   asm volatile("s_waitcnt lgkmcnt(0)" ::: "memory"); SBAR();
	v_mfma_f32_16x16x32_bf16 v[74:77], v[206:209], v[82:85], v[74:77]
	v_exp_f32_e32 v128, v128
	v_mfma_f32_16x16x32_bf16 v[78:81], v[206:209], v[86:89], v[78:81]
	ds_read_b64_tr_b16 v[206:207], v243 offset:40960
	ds_read_b64_tr_b16 v[208:209], v243 offset:45056
	v_exp_f32_e32 v129, v129
	s_waitcnt lgkmcnt(10)
	v_mfma_f32_16x16x32_bf16 v[18:21], v[210:213], v[98:101], v[18:21]
	v_exp_f32_e32 v130, v130
	v_mfma_f32_16x16x32_bf16 v[22:25], v[210:213], v[102:105], v[22:25]
	ds_read_b64_tr_b16 v[210:211], v244 offset:40960
	ds_read_b64_tr_b16 v[212:213], v244 offset:45056
	v_exp_f32_e32 v131, v131
	s_waitcnt lgkmcnt(10)
	v_mfma_f32_16x16x32_bf16 v[26:29], v[214:217], v[98:101], v[26:29]
	v_exp_f32_e32 v132, v132
	v_mfma_f32_16x16x32_bf16 v[30:33], v[214:217], v[102:105], v[30:33]
	ds_read_b64_tr_b16 v[214:215], v245 offset:40960
	ds_read_b64_tr_b16 v[216:217], v245 offset:45056
	v_exp_f32_e32 v133, v133
	s_waitcnt lgkmcnt(10)
	v_mfma_f32_16x16x32_bf16 v[34:37], v[218:221], v[98:101], v[34:37]
	v_exp_f32_e32 v134, v134
	v_mfma_f32_16x16x32_bf16 v[38:41], v[218:221], v[102:105], v[38:41]
	v_exp_f32_e32 v135, v135
	s_waitcnt lgkmcnt(8)
	v_mfma_f32_16x16x32_bf16 v[42:45], v[222:225], v[98:101], v[42:45]
	v_exp_f32_e32 v136, v136
	v_mfma_f32_16x16x32_bf16 v[46:49], v[222:225], v[102:105], v[46:49]
	v_exp_f32_e32 v137, v137
	s_waitcnt lgkmcnt(6)
	v_mfma_f32_16x16x32_bf16 v[50:53], v[202:205], v[98:101], v[50:53]
	v_exp_f32_e32 v138, v138
	v_mfma_f32_16x16x32_bf16 v[54:57], v[202:205], v[102:105], v[54:57]
	v_exp_f32_e32 v139, v139
	s_waitcnt lgkmcnt(4)
	v_mfma_f32_16x16x32_bf16 v[58:61], v[206:209], v[98:101], v[58:61]
	v_exp_f32_e32 v140, v140
	v_mfma_f32_16x16x32_bf16 v[62:65], v[206:209], v[102:105], v[62:65]
	v_exp_f32_e32 v141, v141
	s_waitcnt lgkmcnt(2)
	v_mfma_f32_16x16x32_bf16 v[66:69], v[210:213], v[98:101], v[66:69]
	v_exp_f32_e32 v142, v142
	v_mfma_f32_16x16x32_bf16 v[70:73], v[210:213], v[102:105], v[70:73]
	v_exp_f32_e32 v143, v143
	s_waitcnt lgkmcnt(0)
	v_mfma_f32_16x16x32_bf16 v[74:77], v[214:217], v[98:101], v[74:77]
	v_exp_f32_e32 v144, v144
	v_mfma_f32_16x16x32_bf16 v[78:81], v[214:217], v[102:105], v[78:81]
	v_exp_f32_e32 v145, v145
	s_waitcnt vmcnt(0)
	v_add_f32_e32 v250, v114, v250
	v_add_f32_e32 v250, v115, v250
	v_add_f32_e32 v250, v116, v250
	v_add_f32_e32 v250, v117, v250
	v_add_f32_e32 v250, v122, v250
	v_add_f32_e32 v250, v123, v250
	v_add_f32_e32 v250, v124, v250
	v_add_f32_e32 v250, v125, v250
	v_cvt_pk_bf16_f32 v114, v114, v115
	v_cvt_pk_bf16_f32 v115, v116, v117
	v_cvt_pk_bf16_f32 v116, v122, v123
	v_cvt_pk_bf16_f32 v117, v124, v125
	v_add_f32_e32 v251, v118, v251
	v_add_f32_e32 v251, v119, v251
	v_add_f32_e32 v251, v120, v251
	v_add_f32_e32 v251, v121, v251
	v_add_f32_e32 v251, v126, v251
	v_add_f32_e32 v251, v127, v251
	v_add_f32_e32 v251, v128, v251
	v_add_f32_e32 v251, v129, v251
	v_cvt_pk_bf16_f32 v118, v118, v119
	v_cvt_pk_bf16_f32 v119, v120, v121
	v_cvt_pk_bf16_f32 v120, v126, v127
	v_cvt_pk_bf16_f32 v121, v128, v129
	v_add_f32_e32 v250, v130, v250
	v_add_f32_e32 v250, v131, v250
	v_add_f32_e32 v250, v132, v250
	v_add_f32_e32 v250, v133, v250
	v_add_f32_e32 v250, v138, v250
	v_add_f32_e32 v250, v139, v250
	v_add_f32_e32 v250, v140, v250
	v_add_f32_e32 v250, v141, v250
	v_cvt_pk_bf16_f32 v130, v130, v131
	v_cvt_pk_bf16_f32 v131, v132, v133
	v_cvt_pk_bf16_f32 v132, v138, v139
	v_cvt_pk_bf16_f32 v133, v140, v141
	v_add_f32_e32 v251, v134, v251
	v_add_f32_e32 v251, v135, v251
	v_add_f32_e32 v251, v136, v251
	v_add_f32_e32 v251, v137, v251
	v_add_f32_e32 v251, v142, v251
	v_add_f32_e32 v251, v143, v251
	v_add_f32_e32 v251, v144, v251
	v_add_f32_e32 v251, v145, v251
	v_cvt_pk_bf16_f32 v134, v134, v135
	v_cvt_pk_bf16_f32 v135, v136, v137
	v_cvt_pk_bf16_f32 v136, v142, v143
	v_cvt_pk_bf16_f32 v137, v144, v145
	ds_read_b64_tr_b16 v[202:203], v238 offset:49152
	ds_read_b64_tr_b16 v[204:205], v238 offset:53248
	ds_read_b64_tr_b16 v[206:207], v239 offset:49152
	ds_read_b64_tr_b16 v[208:209], v239 offset:53248
	ds_read_b64_tr_b16 v[210:211], v240 offset:49152
	ds_read_b64_tr_b16 v[212:213], v240 offset:53248
	ds_read_b64_tr_b16 v[214:215], v241 offset:49152
	ds_read_b64_tr_b16 v[216:217], v241 offset:53248
	ds_read_b64_tr_b16 v[218:219], v242 offset:49152
	ds_read_b64_tr_b16 v[220:221], v242 offset:53248
	ds_read_b64_tr_b16 v[222:223], v243 offset:49152
	ds_read_b64_tr_b16 v[224:225], v243 offset:53248
	s_waitcnt lgkmcnt(10)
	v_mfma_f32_16x16x32_bf16 v[18:21], v[202:205], v[114:117], v[18:21]
	v_mfma_f32_16x16x32_bf16 v[22:25], v[202:205], v[118:121], v[22:25]
	ds_read_b64_tr_b16 v[202:203], v244 offset:49152
	ds_read_b64_tr_b16 v[204:205], v244 offset:53248
	s_waitcnt lgkmcnt(10)
	v_mfma_f32_16x16x32_bf16 v[26:29], v[206:209], v[114:117], v[26:29]
	v_mfma_f32_16x16x32_bf16 v[30:33], v[206:209], v[118:121], v[30:33]
	ds_read_b64_tr_b16 v[206:207], v245 offset:49152
	ds_read_b64_tr_b16 v[208:209], v245 offset:53248
	s_waitcnt lgkmcnt(10)
	v_mfma_f32_16x16x32_bf16 v[34:37], v[210:213], v[114:117], v[34:37]
	v_mfma_f32_16x16x32_bf16 v[38:41], v[210:213], v[118:121], v[38:41]
	ds_read_b64_tr_b16 v[210:211], v238 offset:57344
	ds_read_b64_tr_b16 v[212:213], v238 offset:61440
	s_waitcnt lgkmcnt(10)
	v_mfma_f32_16x16x32_bf16 v[42:45], v[214:217], v[114:117], v[42:45]
	v_mfma_f32_16x16x32_bf16 v[46:49], v[214:217], v[118:121], v[46:49]
	ds_read_b64_tr_b16 v[214:215], v239 offset:57344
	ds_read_b64_tr_b16 v[216:217], v239 offset:61440
	s_waitcnt lgkmcnt(10)
	v_mfma_f32_16x16x32_bf16 v[50:53], v[218:221], v[114:117], v[50:53]
	v_mfma_f32_16x16x32_bf16 v[54:57], v[218:221], v[118:121], v[54:57]
	ds_read_b64_tr_b16 v[218:219], v240 offset:57344
	ds_read_b64_tr_b16 v[220:221], v240 offset:61440
	s_waitcnt lgkmcnt(10)
; #define SBAR() __builtin_amdgcn_sched_barrier(0)
; __device__ __forceinline__ int crow(int r, int hi) { return (r & 3) + 8 * (r >> 2) + 4 * hi; }
; template <typename TQ> ...
;     ...
;   finishSM(pB0, pB1, l_reg, pa0, pa1, pa2, pa3); SBAR();
;   pv_d0(o, vb0 + (int)SHM_V, pa0, pa1, pa2, pa3);
;   if (hi == 0) li_l[r32] = l_reg; asm volatile("s_waitcnt lgkmcnt(0)" ::: "memory");
;   float rli[16];
; #pragma unroll
;   for (int r = 0; r < 16; ++r) rli[r] = __builtin_amdgcn_rcpf(li_l[crow(r, hi)]);
;   int le = (int)(threadIdx.x & 63u); asm volatile("" : "+v"(le));
;   const int r32e = le & 31, hie = le >> 5;
;   bf16* Ow = Ob + (long)(wid * QBLK) * LDO;
; #pragma unroll
;   for (int r = 0; r < 16; ++r) { int orow = crow(r, hie);
;     for (int d0 = 0; d0 < 4; ++d0) Ow[(long)orow * LDO + d0 * 32 + r32e] = __float2bfloat16(o[d0][r] * rli[r]); }
; __global__ void __launch_bounds__(NTHR, 2) fwd_megakernel(KArgs a) {
;     ...
;         for (int i = 0; i < upb; ++i) {
;             const int unit = vcu * upb + i; if (unit >= 512) break;
;             const int grp = unit >> 7, rem = unit & 127, gq = rem >> 5, qb = rem & 31, b = grp >> 1, kvh = grp & 1, h = kvh * 4 + gq;
;             const size_t qoff = ((size_t)(b * SEQ + qb * 256)) * DM + h * 128, koff = (size_t)b * SKV * 256 + kvh * 128;
;             att::attn_dense_body<att::bf16>(Q + qoff, Kb + koff, Vb + koff, O + qoff, SKV, (char*)lds_raw, mC, a.g_q, (const float*)(ws + WS_ROPE), (const float*)(ws + WS_ROPE) + 4096, qb * 256);
;             __syncthreads();
;         }
	v_mfma_f32_16x16x32_bf16 v[58:61], v[222:225], v[114:117], v[58:61]
	v_mfma_f32_16x16x32_bf16 v[62:65], v[222:225], v[118:121], v[62:65]
	ds_read_b64_tr_b16 v[222:223], v241 offset:57344
	ds_read_b64_tr_b16 v[224:225], v241 offset:61440
	s_waitcnt lgkmcnt(10)
	v_mfma_f32_16x16x32_bf16 v[66:69], v[202:205], v[114:117], v[66:69]
	v_mfma_f32_16x16x32_bf16 v[70:73], v[202:205], v[118:121], v[70:73]
	ds_read_b64_tr_b16 v[202:203], v242 offset:57344
	ds_read_b64_tr_b16 v[204:205], v242 offset:61440
	s_waitcnt lgkmcnt(10)
	v_mfma_f32_16x16x32_bf16 v[74:77], v[206:209], v[114:117], v[74:77]
	v_mfma_f32_16x16x32_bf16 v[78:81], v[206:209], v[118:121], v[78:81]
	ds_read_b64_tr_b16 v[206:207], v243 offset:57344
	ds_read_b64_tr_b16 v[208:209], v243 offset:61440
	s_waitcnt lgkmcnt(10)
	v_mfma_f32_16x16x32_bf16 v[18:21], v[210:213], v[130:133], v[18:21]
	v_mfma_f32_16x16x32_bf16 v[22:25], v[210:213], v[134:137], v[22:25]
	ds_read_b64_tr_b16 v[210:211], v244 offset:57344
	ds_read_b64_tr_b16 v[212:213], v244 offset:61440
	s_waitcnt lgkmcnt(10)
	v_mfma_f32_16x16x32_bf16 v[26:29], v[214:217], v[130:133], v[26:29]
	v_mfma_f32_16x16x32_bf16 v[30:33], v[214:217], v[134:137], v[30:33]
	ds_read_b64_tr_b16 v[214:215], v245 offset:57344
	ds_read_b64_tr_b16 v[216:217], v245 offset:61440
	s_waitcnt lgkmcnt(10)
	v_mfma_f32_16x16x32_bf16 v[34:37], v[218:221], v[130:133], v[34:37]
	v_mfma_f32_16x16x32_bf16 v[38:41], v[218:221], v[134:137], v[38:41]
	s_waitcnt lgkmcnt(8)
	v_mfma_f32_16x16x32_bf16 v[42:45], v[222:225], v[130:133], v[42:45]
	v_mfma_f32_16x16x32_bf16 v[46:49], v[222:225], v[134:137], v[46:49]
	s_waitcnt lgkmcnt(6)
	v_mfma_f32_16x16x32_bf16 v[50:53], v[202:205], v[130:133], v[50:53]
	v_mfma_f32_16x16x32_bf16 v[54:57], v[202:205], v[134:137], v[54:57]
	s_waitcnt lgkmcnt(4)
	v_mfma_f32_16x16x32_bf16 v[58:61], v[206:209], v[130:133], v[58:61]
	v_mfma_f32_16x16x32_bf16 v[62:65], v[206:209], v[134:137], v[62:65]
	s_waitcnt lgkmcnt(2)
	v_mfma_f32_16x16x32_bf16 v[66:69], v[210:213], v[130:133], v[66:69]
	v_mfma_f32_16x16x32_bf16 v[70:73], v[210:213], v[134:137], v[70:73]
	s_waitcnt lgkmcnt(0)
	v_mfma_f32_16x16x32_bf16 v[74:77], v[214:217], v[130:133], v[74:77]
	v_mfma_f32_16x16x32_bf16 v[78:81], v[214:217], v[134:137], v[78:81]
	s_setprio 0
	ds_swizzle_b32 v6, v250 offset:swizzle(SWAP,16)
	s_waitcnt lgkmcnt(0)
	v_add_f32_e32 v250, v250, v6
	v_mov_b32_e32 v6, v250
	s_nop 1
	v_permlane32_swap_b32_e32 v250, v6
	v_add_f32_e32 v250, v250, v6
	v_rcp_f32_e32 v250, v250
	ds_swizzle_b32 v6, v251 offset:swizzle(SWAP,16)
	s_waitcnt lgkmcnt(0)
	v_add_f32_e32 v251, v251, v6
	v_mov_b32_e32 v6, v251
	s_nop 1
	v_permlane32_swap_b32_e32 v251, v6
	v_add_f32_e32 v251, v251, v6
	v_rcp_f32_e32 v251, v251
	s_add_u32 s12, s71, s48
	s_addc_u32 s13, s72, s49
	v_add_u32_e32 v201, s52, v16
	v_lshlrev_b32_e32 v201, 11, v201
	v_lshl_or_b32 v7, v17, 3, v201
	v_add_u32_e32 v200, 0x8000, v7
	v_mul_f32_e32 v18, v18, v250
	v_mul_f32_e32 v19, v19, v250
	v_mul_f32_e32 v20, v20, v250
	v_mul_f32_e32 v21, v21, v250
	v_cvt_pk_bf16_f32 v18, v18, v19
	v_cvt_pk_bf16_f32 v19, v20, v21
	global_store_dwordx2 v7, v[18:19], s[12:13] offset:0
	v_mul_f32_e32 v22, v22, v251
	v_mul_f32_e32 v23, v23, v251
	v_mul_f32_e32 v24, v24, v251
	v_mul_f32_e32 v25, v25, v251
	v_cvt_pk_bf16_f32 v22, v22, v23
	v_cvt_pk_bf16_f32 v23, v24, v25
	global_store_dwordx2 v200, v[22:23], s[12:13] offset:0
	v_mul_f32_e32 v26, v26, v250
	v_mul_f32_e32 v27, v27, v250
	v_mul_f32_e32 v28, v28, v250
	v_mul_f32_e32 v29, v29, v250
	v_cvt_pk_bf16_f32 v26, v26, v27
	v_cvt_pk_bf16_f32 v27, v28, v29
	global_store_dwordx2 v7, v[26:27], s[12:13] offset:32
	v_mul_f32_e32 v30, v30, v251
	v_mul_f32_e32 v31, v31, v251
	v_mul_f32_e32 v32, v32, v251
	v_mul_f32_e32 v33, v33, v251
	v_cvt_pk_bf16_f32 v30, v30, v31
	v_cvt_pk_bf16_f32 v31, v32, v33
	global_store_dwordx2 v200, v[30:31], s[12:13] offset:32
	v_mul_f32_e32 v34, v34, v250
	v_mul_f32_e32 v35, v35, v250
	v_mul_f32_e32 v36, v36, v250
	v_mul_f32_e32 v37, v37, v250
	v_cvt_pk_bf16_f32 v34, v34, v35
	v_cvt_pk_bf16_f32 v35, v36, v37
	global_store_dwordx2 v7, v[34:35], s[12:13] offset:64
	v_mul_f32_e32 v38, v38, v251
	v_mul_f32_e32 v39, v39, v251
	v_mul_f32_e32 v40, v40, v251
	v_mul_f32_e32 v41, v41, v251
	v_cvt_pk_bf16_f32 v38, v38, v39
	v_cvt_pk_bf16_f32 v39, v40, v41
	global_store_dwordx2 v200, v[38:39], s[12:13] offset:64
	v_mul_f32_e32 v42, v42, v250
	v_mul_f32_e32 v43, v43, v250
	v_mul_f32_e32 v44, v44, v250
	v_mul_f32_e32 v45, v45, v250
	v_cvt_pk_bf16_f32 v42, v42, v43
	v_cvt_pk_bf16_f32 v43, v44, v45
	global_store_dwordx2 v7, v[42:43], s[12:13] offset:96
	v_mul_f32_e32 v46, v46, v251
	v_mul_f32_e32 v47, v47, v251
	v_mul_f32_e32 v48, v48, v251
	v_mul_f32_e32 v49, v49, v251
	v_cvt_pk_bf16_f32 v46, v46, v47
	v_cvt_pk_bf16_f32 v47, v48, v49
	global_store_dwordx2 v200, v[46:47], s[12:13] offset:96
	v_mul_f32_e32 v50, v50, v250
	v_mul_f32_e32 v51, v51, v250
	v_mul_f32_e32 v52, v52, v250
	v_mul_f32_e32 v53, v53, v250
	v_cvt_pk_bf16_f32 v50, v50, v51
	v_cvt_pk_bf16_f32 v51, v52, v53
	global_store_dwordx2 v7, v[50:51], s[12:13] offset:128
	v_mul_f32_e32 v54, v54, v251
	v_mul_f32_e32 v55, v55, v251
	v_mul_f32_e32 v56, v56, v251
	v_mul_f32_e32 v57, v57, v251
	v_cvt_pk_bf16_f32 v54, v54, v55
	v_cvt_pk_bf16_f32 v55, v56, v57
	global_store_dwordx2 v200, v[54:55], s[12:13] offset:128
	v_mul_f32_e32 v58, v58, v250
	v_mul_f32_e32 v59, v59, v250
	v_mul_f32_e32 v60, v60, v250
	v_mul_f32_e32 v61, v61, v250
	v_cvt_pk_bf16_f32 v58, v58, v59
	v_cvt_pk_bf16_f32 v59, v60, v61
	global_store_dwordx2 v7, v[58:59], s[12:13] offset:160
	v_mul_f32_e32 v62, v62, v251
	v_mul_f32_e32 v63, v63, v251
	v_mul_f32_e32 v64, v64, v251
	v_mul_f32_e32 v65, v65, v251
	v_cvt_pk_bf16_f32 v62, v62, v63
	v_cvt_pk_bf16_f32 v63, v64, v65
	global_store_dwordx2 v200, v[62:63], s[12:13] offset:160
	v_mul_f32_e32 v66, v66, v250
	v_mul_f32_e32 v67, v67, v250
	v_mul_f32_e32 v68, v68, v250
	v_mul_f32_e32 v69, v69, v250
	v_cvt_pk_bf16_f32 v66, v66, v67
	v_cvt_pk_bf16_f32 v67, v68, v69
	global_store_dwordx2 v7, v[66:67], s[12:13] offset:192
	v_mul_f32_e32 v70, v70, v251
	v_mul_f32_e32 v71, v71, v251
	v_mul_f32_e32 v72, v72, v251
	v_mul_f32_e32 v73, v73, v251
	v_cvt_pk_bf16_f32 v70, v70, v71
	v_cvt_pk_bf16_f32 v71, v72, v73
	global_store_dwordx2 v200, v[70:71], s[12:13] offset:192
	v_mul_f32_e32 v74, v74, v250
	v_mul_f32_e32 v75, v75, v250
	v_mul_f32_e32 v76, v76, v250
	v_mul_f32_e32 v77, v77, v250
	v_cvt_pk_bf16_f32 v74, v74, v75
	v_cvt_pk_bf16_f32 v75, v76, v77
	global_store_dwordx2 v7, v[74:75], s[12:13] offset:224
	v_mul_f32_e32 v78, v78, v251
	v_mul_f32_e32 v79, v79, v251
	v_mul_f32_e32 v80, v80, v251
	v_mul_f32_e32 v81, v81, v251
	v_cvt_pk_bf16_f32 v78, v78, v79
	v_cvt_pk_bf16_f32 v79, v80, v81
	global_store_dwordx2 v200, v[78:79], s[12:13] offset:224
	s_add_i32 s74, s74, 1
	s_add_i32 s94, s94, 1
	s_cmp_eq_u32 s74, s66
	s_cselect_b64 s[0:1], -1, 0
	s_barrier
	s_branch .LBB0_818
